# RNN scan-product byte emission: 4x4 byte transpose across lane quads, one 32-bit LDS store replaces four 8-bit stores (same LDS image), on top of group-of-4 tile swizzle
# baseline (speedup 1.0000x reference)
; __device__ __forceinline__ void rnn_local_phase(Frame& F, const XcdBarrier& gbar, const bool use_bar) {
;     ...
;     bf16x8 idf;
;     { const bool on = (8 * fq) == ((16 * (w & 1) + fr) & ~7);
; #pragma unroll
;       for (int jj = 0; jj < 8; ++jj) idf[jj] = (short)((on && jj == (fr & 7)) ? 0x3F80 : 0); }
;     const int ksx = w >> 1;
;     float nba[2], nbx[2], kap[2];
; #pragma unroll
;     for (int dir = 0; dir < 2; ++dir) {
;         nba[dir] = -LOG2E * F.lru_ba[dir * DRNN + c]; nbx[dir] = -LOG2E * F.lru_bx[dir * DRNN + c];
;         const float lm = F.lam[dir * DRNN + c];
;         const float sp = fmaxf(-lm, 0.f) + log1pf(expf(-fabsf(lm)));
;         kap[dir] = -8.0f * sp * LOG2E;
;     }
;     const int cp = tid & 63;
;     float cw[4][2], cbias[2];
;     { const int cc = cb * 128 + 2 * cp;
; #pragma unroll
;       for (int jj = 0; jj < 4; ++jj) { cw[jj][0] = F.conv_w[jj * DRNN + cc]; cw[jj][1] = F.conv_w[jj * DRNN + cc + 1]; }
;       cbias[0] = F.conv_b[cc]; cbias[1] = F.conv_b[cc + 1]; }
.LBB0_613:
	s_andn2_b64 vcc, exec, s[16:17]
	s_waitcnt vmcnt(0) lgkmcnt(0)
	s_barrier
	s_cbranch_vccnz .LBB0_625
	s_sub_i32 s0, s3, s0
	s_add_i32 s0, s0, 9
	s_add_u32 s9, s10, 0x2100000
	s_mul_hi_i32 s0, s0, 0x66666667
	v_and_b32_e32 v67, 24, v84
	s_addc_u32 s12, s11, 0
	s_lshr_b32 s1, s0, 31
	s_ashr_i32 s13, s0, 2
	v_cmp_eq_u32_e32 vcc, v64, v67
	v_and_b32_e32 v64, 7, v70
	s_add_i32 s13, s13, s1
	v_cmp_eq_u32_e64 s[0:1], 0, v64
	v_mov_b32_e32 v67, 0x3f80
	s_and_b64 s[0:1], s[0:1], vcc
	v_cndmask_b32_e64 v69, 0, v67, s[0:1]
	v_cmp_eq_u32_e64 s[0:1], 1, v64
	s_and_b64 s[0:1], s[0:1], vcc
	s_mov_b32 s2, 0xb2a5705f
	v_cndmask_b32_e64 v79, 0, v67, s[0:1]
	v_cmp_eq_u32_e64 s[0:1], 2, v64
	s_and_b64 s[0:1], s[0:1], vcc
	s_mov_b32 s4, 0x42ce8ed0
	v_cndmask_b32_e64 v80, 0, v67, s[0:1]
	v_cmp_eq_u32_e64 s[0:1], 3, v64
	s_and_b64 s[0:1], s[0:1], vcc
	s_mov_b32 s5, 0xc2b17218
	v_cndmask_b32_e64 v81, 0, v67, s[0:1]
	v_cmp_eq_u32_e64 s[0:1], 4, v64
	s_and_b64 s[0:1], s[0:1], vcc
	v_mov_b32_e32 v88, 0x7f800000
	v_cndmask_b32_e64 v82, 0, v67, s[0:1]
	v_cmp_eq_u32_e64 s[0:1], 5, v64
	s_and_b64 s[0:1], s[0:1], vcc
	s_mov_b32 s7, 0x3f2aaaab
	v_cndmask_b32_e64 v85, 0, v67, s[0:1]
	v_cmp_eq_u32_e64 s[0:1], 6, v64
	s_and_b64 s[0:1], s[0:1], vcc
	s_mov_b32 s14, 0x3f317218
	v_cndmask_b32_e64 v83, 0, v67, s[0:1]
	v_cmp_eq_u32_e64 s[0:1], 7, v64
	s_and_b64 vcc, s[0:1], vcc
	s_mov_b32 s1, 0xbfb8aa3b
	v_cndmask_b32_e32 v87, 0, v67, vcc
	v_mul_f32_e64 v67, |v76|, s1
	v_rndne_f32_e32 v68, v67
	v_sub_f32_e32 v75, v67, v68
	v_fma_f32 v67, |v76|, s1, -v67
	v_fma_f32 v67, |v76|, s2, v67
	v_add_f32_e32 v67, v75, v67
	v_exp_f32_e32 v67, v67
	v_cvt_i32_f32_e32 v75, v68
	v_cmp_ngt_f32_e64 vcc, |v76|, s4
	v_mul_f32_e32 v64, 0xbfb8aa3b, v77
	v_max_f32_e64 v77, -v76, -v76
	v_ldexp_f32 v67, v67, v75
	v_cndmask_b32_e32 v67, 0, v67, vcc
	v_cmp_nlt_f32_e64 vcc, |v76|, s5
	v_mul_f32_e32 v68, 0xbfb8aa3b, v78
	v_max_f32_e32 v78, 0, v77
	v_cndmask_b32_e32 v67, v88, v67, vcc
	v_add_f32_e32 v75, 1.0, v67
	v_add_f32_e32 v76, -1.0, v75
	v_sub_f32_e32 v77, v76, v75
	v_add_f32_e32 v77, 1.0, v77
	v_sub_f32_e32 v76, v67, v76
	v_add_f32_e32 v89, v76, v77
	v_frexp_mant_f32_e32 v90, v75
	v_cvt_f64_f32_e32 v[76:77], v75
	v_frexp_exp_i32_f64_e32 v76, v[76:77]
	v_cmp_gt_f32_e32 vcc, s7, v90
	s_mov_b32 s0, 0x7f800000
	s_mov_b32 s15, 0x33800000
	v_subbrev_co_u32_e32 v76, vcc, 0, v76, vcc
	v_sub_u32_e32 v77, 0, v76
	v_ldexp_f32 v75, v75, v77
	v_ldexp_f32 v77, v89, v77
	v_add_f32_e32 v89, -1.0, v75
	v_add_f32_e32 v92, 1.0, v75
	v_add_f32_e32 v90, 1.0, v89
	v_add_f32_e32 v93, -1.0, v92
	v_sub_f32_e32 v90, v75, v90
	v_sub_f32_e32 v75, v75, v93
	v_add_f32_e32 v75, v77, v75
	v_add_f32_e32 v90, v77, v90
	v_add_f32_e32 v77, v92, v75
	v_rcp_f32_e32 v93, v77
	v_add_f32_e32 v91, v89, v90
	v_sub_f32_e32 v89, v89, v91
	v_add_f32_e32 v89, v90, v89
	v_sub_f32_e32 v90, v92, v77
	v_add_f32_e32 v75, v75, v90
	v_mul_f32_e32 v90, v91, v93
	v_mul_f32_e32 v92, v77, v90
	v_fma_f32 v94, v90, v77, -v92
	v_fmac_f32_e32 v94, v90, v75
	v_add_f32_e32 v95, v92, v94
	v_sub_f32_e32 v96, v91, v95
	v_sub_f32_e32 v91, v91, v96
	v_sub_f32_e32 v92, v95, v92
	v_sub_f32_e32 v91, v91, v95
	v_add_f32_e32 v89, v89, v91
	v_sub_f32_e32 v91, v92, v94
	v_add_f32_e32 v89, v91, v89
	v_add_f32_e32 v91, v96, v89
	v_mul_f32_e32 v92, v93, v91
	v_mul_f32_e32 v94, v77, v92
	v_fma_f32 v77, v92, v77, -v94
	v_fmac_f32_e32 v77, v92, v75
	v_sub_f32_e32 v75, v96, v91
	v_add_f32_e32 v75, v89, v75
	v_add_f32_e32 v89, v94, v77
	v_sub_f32_e32 v95, v91, v89
	v_sub_f32_e32 v91, v91, v95
	v_sub_f32_e32 v94, v89, v94
	v_sub_f32_e32 v89, v91, v89
	v_add_f32_e32 v75, v75, v89
	v_sub_f32_e32 v77, v94, v77
	v_cvt_f32_i32_e32 v76, v76
	v_add_f32_e32 v75, v77, v75
	v_add_f32_e32 v77, v90, v92
	v_add_f32_e32 v75, v95, v75
	v_sub_f32_e32 v89, v77, v90
	v_mul_f32_e32 v75, v93, v75
	v_sub_f32_e32 v89, v92, v89
	v_add_f32_e32 v75, v89, v75
	v_mul_f32_e32 v94, 0x3f317218, v76
	v_add_f32_e32 v89, v77, v75
	v_fma_f32 v95, v76, s14, -v94
	v_mul_f32_e32 v90, v89, v89
	v_mov_b32_e32 v91, 0x3ecc95a3
	v_fmac_f32_e32 v95, 0xb102e308, v76
	v_sub_f32_e32 v76, v89, v77
	v_fmamk_f32 v92, v90, 0x3e9b6dac, v91
	v_sub_f32_e32 v75, v75, v76
	v_add_f32_e32 v76, v94, v95
	v_fmaak_f32 v92, v90, v92, 0x3f2aaada
	v_sub_f32_e32 v77, v76, v94
	v_ldexp_f32 v94, v89, 1
	v_mul_f32_e32 v89, v89, v90
	v_mul_f32_e32 v89, v89, v92
	v_add_f32_e32 v90, v94, v89
	v_sub_f32_e32 v92, v90, v94
	v_ldexp_f32 v75, v75, 1
	v_sub_f32_e32 v89, v89, v92
	v_add_f32_e32 v75, v75, v89
	v_add_f32_e32 v89, v90, v75
	v_sub_f32_e32 v90, v89, v90
	v_sub_f32_e32 v75, v75, v90
	v_add_f32_e32 v90, v76, v89
	v_sub_f32_e32 v92, v90, v76
	v_sub_f32_e32 v94, v90, v92
	v_sub_f32_e32 v77, v95, v77
	v_sub_f32_e32 v76, v76, v94
	v_sub_f32_e32 v89, v89, v92
	v_add_f32_e32 v76, v89, v76
	v_add_f32_e32 v89, v77, v75
	v_sub_f32_e32 v92, v89, v77
	v_sub_f32_e32 v94, v89, v92
	v_sub_f32_e32 v77, v77, v94
	v_sub_f32_e32 v75, v75, v92
	v_add_f32_e32 v76, v89, v76
	v_add_f32_e32 v75, v75, v77
	v_add_f32_e32 v77, v90, v76
	v_sub_f32_e32 v89, v77, v90
	v_sub_f32_e32 v76, v76, v89
	v_add_f32_e32 v75, v75, v76
	v_add_f32_e32 v75, v77, v75
	v_cmp_neq_f32_e32 vcc, s0, v67
	v_mov_b32_e32 v93, 0x3f2aaada
	v_readlane_b32 s21, v254, 4
	v_cndmask_b32_e32 v75, v88, v75, vcc
	v_cmp_lt_f32_e64 vcc, |v67|, s15
	v_mov_b32_e32 v172, 0
	v_mul_f32_e32 v72, 0xbfb8aa3b, v72
	v_cndmask_b32_e32 v67, v75, v67, vcc
	v_add_f32_e32 v67, v78, v67
	v_mul_f32_e32 v67, 0xc1000000, v67
	v_mul_f32_e32 v160, 0x3fb8aa3b, v67
	v_mul_f32_e64 v67, |v71|, s1
	v_rndne_f32_e32 v75, v67
	v_sub_f32_e32 v76, v67, v75
	v_fma_f32 v67, |v71|, s1, -v67
	v_fma_f32 v67, |v71|, s2, v67
; __device__ __forceinline__ void rnn_local_phase(Frame& F, const XcdBarrier& gbar, const bool use_bar) {
;     ...
;     for (int dir = 0; dir < 2; ++dir) {
;         nba[dir] = -LOG2E * F.lru_ba[dir * DRNN + c]; nbx[dir] = -LOG2E * F.lru_bx[dir * DRNN + c];
;         const float lm = F.lam[dir * DRNN + c];
;         const float sp = fmaxf(-lm, 0.f) + log1pf(expf(-fabsf(lm)));
;         kap[dir] = -8.0f * sp * LOG2E;
;     }
;     const int cp = tid & 63;
;     float cw[4][2], cbias[2];
;     { const int cc = cb * 128 + 2 * cp;
; #pragma unroll
;       for (int jj = 0; jj < 4; ++jj) { cw[jj][0] = F.conv_w[jj * DRNN + cc]; cw[jj][1] = F.conv_w[jj * DRNN + cc + 1]; }
;       cbias[0] = F.conv_b[cc]; cbias[1] = F.conv_b[cc + 1]; }
;     const float mk0 = fq == 0 ? 1.f : 0.f, mk1 = fq == 1 ? 1.f : 0.f, mk2 = fq == 2 ? 1.f : 0.f, mk3 = fq == 3 ? 1.f : 0.f;
;     ...
;     int q = rank;
;     if (q < NQ) RNN_DMA(q);
;     if (use_bar) xcd_wait(gbar, tok);
;     __builtin_amdgcn_s_waitcnt(0x0F70);
;     __syncthreads();
;     for (; q < NQ; q += cnt) {
	v_add_f32_e32 v67, v76, v67
	v_exp_f32_e32 v67, v67
	v_cvt_i32_f32_e32 v75, v75
	v_cmp_ngt_f32_e64 vcc, |v71|, s4
	v_mul_f32_e32 v76, 0xbfb8aa3b, v74
	v_max_f32_e64 v74, -v71, -v71
	v_ldexp_f32 v67, v67, v75
	v_cndmask_b32_e32 v67, 0, v67, vcc
	v_cmp_nlt_f32_e64 vcc, |v71|, s5
	v_max_f32_e32 v77, 0, v74
	v_readlane_b32 s2, v254, 5
	v_cndmask_b32_e32 v67, v88, v67, vcc
	v_add_f32_e32 v71, 1.0, v67
	v_add_f32_e32 v74, -1.0, v71
	v_sub_f32_e32 v75, v74, v71
	v_add_f32_e32 v75, 1.0, v75
	v_sub_f32_e32 v74, v67, v74
	v_add_f32_e32 v78, v74, v75
	v_frexp_mant_f32_e32 v89, v71
	v_cvt_f64_f32_e32 v[74:75], v71
	v_frexp_exp_i32_f64_e32 v74, v[74:75]
	v_cmp_gt_f32_e32 vcc, s7, v89
	s_mov_b32 s17, 0
	v_mov_b32_e32 v161, v160
	v_subbrev_co_u32_e32 v74, vcc, 0, v74, vcc
	v_sub_u32_e32 v75, 0, v74
	v_ldexp_f32 v71, v71, v75
	v_ldexp_f32 v75, v78, v75
	v_add_f32_e32 v78, -1.0, v71
	v_add_f32_e32 v92, 1.0, v71
	v_add_f32_e32 v89, 1.0, v78
	v_add_f32_e32 v94, -1.0, v92
	v_sub_f32_e32 v89, v71, v89
	v_sub_f32_e32 v71, v71, v94
	v_add_f32_e32 v71, v75, v71
	v_add_f32_e32 v89, v75, v89
	v_add_f32_e32 v75, v92, v71
	v_rcp_f32_e32 v94, v75
	v_add_f32_e32 v90, v78, v89
	v_sub_f32_e32 v78, v78, v90
	v_add_f32_e32 v78, v89, v78
	v_sub_f32_e32 v89, v92, v75
	v_add_f32_e32 v71, v71, v89
	v_mul_f32_e32 v89, v90, v94
	v_mul_f32_e32 v92, v75, v89
	v_fma_f32 v95, v89, v75, -v92
	v_fmac_f32_e32 v95, v89, v71
	v_add_f32_e32 v96, v92, v95
	v_sub_f32_e32 v97, v90, v96
	v_sub_f32_e32 v90, v90, v97
	v_sub_f32_e32 v92, v96, v92
	v_sub_f32_e32 v90, v90, v96
	v_add_f32_e32 v78, v78, v90
	v_sub_f32_e32 v90, v92, v95
	v_add_f32_e32 v78, v90, v78
	v_add_f32_e32 v90, v97, v78
	v_mul_f32_e32 v92, v94, v90
	v_mul_f32_e32 v95, v75, v92
	v_fma_f32 v75, v92, v75, -v95
	v_fmac_f32_e32 v75, v92, v71
	v_sub_f32_e32 v71, v97, v90
	v_add_f32_e32 v71, v78, v71
	v_add_f32_e32 v78, v95, v75
	v_sub_f32_e32 v96, v90, v78
	v_sub_f32_e32 v90, v90, v96
	v_sub_f32_e32 v95, v78, v95
	v_sub_f32_e32 v78, v90, v78
	v_add_f32_e32 v71, v71, v78
	v_sub_f32_e32 v75, v95, v75
	v_add_f32_e32 v71, v75, v71
	v_add_f32_e32 v75, v89, v92
	v_add_f32_e32 v71, v96, v71
	v_sub_f32_e32 v78, v75, v89
	v_mul_f32_e32 v71, v94, v71
	v_sub_f32_e32 v78, v92, v78
	v_cvt_f32_i32_e32 v74, v74
	v_add_f32_e32 v71, v78, v71
	v_add_f32_e32 v78, v75, v71
	v_mul_f32_e32 v89, v78, v78
	v_fmac_f32_e32 v91, 0x3e9b6dac, v89
	v_mul_f32_e32 v90, 0x3f317218, v74
	v_fmac_f32_e32 v93, v89, v91
	v_fma_f32 v91, v74, s14, -v90
	v_fmac_f32_e32 v91, 0xb102e308, v74
	v_sub_f32_e32 v74, v78, v75
	v_sub_f32_e32 v71, v71, v74
	v_add_f32_e32 v74, v90, v91
	v_sub_f32_e32 v75, v74, v90
	v_ldexp_f32 v90, v78, 1
	v_mul_f32_e32 v78, v78, v89
	v_mul_f32_e32 v78, v78, v93
	v_add_f32_e32 v89, v90, v78
	v_sub_f32_e32 v90, v89, v90
	v_ldexp_f32 v71, v71, 1
	v_sub_f32_e32 v78, v78, v90
	v_add_f32_e32 v71, v71, v78
	v_add_f32_e32 v78, v89, v71
	v_sub_f32_e32 v89, v78, v89
	v_sub_f32_e32 v71, v71, v89
	v_add_f32_e32 v89, v74, v78
	v_sub_f32_e32 v90, v89, v74
	v_sub_f32_e32 v75, v91, v75
	v_sub_f32_e32 v91, v89, v90
	v_sub_f32_e32 v74, v74, v91
	v_sub_f32_e32 v78, v78, v90
	v_add_f32_e32 v74, v78, v74
	v_add_f32_e32 v78, v75, v71
	v_sub_f32_e32 v90, v78, v75
	v_sub_f32_e32 v91, v78, v90
	v_sub_f32_e32 v75, v75, v91
	v_sub_f32_e32 v71, v71, v90
	v_add_f32_e32 v74, v78, v74
	v_add_f32_e32 v71, v71, v75
	v_add_f32_e32 v75, v89, v74
	v_sub_f32_e32 v78, v75, v89
	v_sub_f32_e32 v74, v74, v78
	v_add_f32_e32 v71, v71, v74
	v_add_u32_e32 v90, s2, v70
	s_lshl_b32 s2, s21, 11
	v_add_f32_e32 v71, v75, v71
	v_cmp_neq_f32_e32 vcc, s0, v67
	s_add_i32 s2, s2, 0
	s_add_i32 s16, s2, 0x10000
	v_cndmask_b32_e32 v71, v88, v71, vcc
	v_cmp_lt_f32_e64 vcc, |v67|, s15
	s_cmp_eq_u32 s21, 7
	s_cselect_b64 s[4:5], -1, 0
	v_cndmask_b32_e32 v67, v71, v67, vcc
	v_add_f32_e32 v67, v77, v67
	s_ashr_i32 s7, s6, 31
	v_mul_f32_e32 v67, 0xc1000000, v67
	s_lshl_b32 s20, s21, 3
	s_lshl_b64 s[14:15], s[6:7], 1
	v_mul_f32_e32 v162, 0x3fb8aa3b, v67
	v_lshlrev_b32_e32 v67, 2, v70
	s_add_u32 s18, s33, s14
	v_and_b32_e32 v92, 12, v67
	s_addc_u32 s19, s34, s15
	v_mov_b32_e32 v67, v172
	v_lshl_add_u64 v[174:175], s[18:19], 0, v[66:67]
	s_lshl_b32 s18, s21, 1
	s_and_b32 s18, s18, 0x7fffffc
	s_add_u32 s14, s10, s14
	s_addc_u32 s15, s11, s15
	v_lshl_add_u64 v[66:67], s[14:15], 0, v[66:67]
	s_mov_b64 s[14:15], 0xe000000
	v_lshlrev_b32_e32 v91, 2, v65
	v_lshrrev_b32_e32 v65, 2, v65
	v_lshl_add_u64 v[176:177], v[66:67], 0, s[14:15]
	v_lshlrev_b32_e32 v66, 4, v70
	s_add_u32 s6, s10, s6
	v_and_b32_e32 v88, 0x70, v66
	s_addc_u32 s7, s11, s7
	v_mov_b32_e32 v89, v172
; #define LAS __attribute__((address_space(3)))
; __device__ __forceinline__ void rnn_local_phase(Frame& F, const XcdBarrier& gbar, const bool use_bar) {
;     ...
;     const float mk0 = fq == 0 ? 1.f : 0.f, mk1 = fq == 1 ? 1.f : 0.f, mk2 = fq == 2 ? 1.f : 0.f, mk3 = fq == 3 ? 1.f : 0.f;
;     ...
;     int q = rank;
;     if (q < NQ) RNN_DMA(q);
;     if (use_bar) xcd_wait(gbar, tok);
;     __builtin_amdgcn_s_waitcnt(0x0F70);
;     __syncthreads();
;     for (; q < NQ; q += cnt) {
;         const int b = q / NCH, j = q % NCH, t0 = b * SEQ + j * LCH;
;         const bool has_next = (q + cnt) < NQ;
;         {
;             float x0[11], x1[11];
; #pragma unroll
;             for (int r = 0; r < 11; ++r) { const unsigned v = *(const LAS unsigned*)(lds + R_RAW_OFF + (8 * w + r) * 256 + cp * 4); x0[r] = bflo(v); x1[r] = bfhi(v); }
;             if (j == 0 && w == 0) { x0[0] = 0.f; x1[0] = 0.f; x0[1] = 0.f; x1[1] = 0.f; }
;             if (j == NCH - 1 && w == NWAVES - 1) { x0[10] = 0.f; x1[10] = 0.f; }
; #pragma unroll
;             for (int t8 = 0; t8 < 8; ++t8) {
;                 const int tt = 8 * w + t8;
;                 float y0 = cbias[0], y1 = cbias[1];
; #pragma unroll
;                 for (int jj = 0; jj < 4; ++jj) { y0 += cw[jj][0] * x0[t8 + jj]; y1 += cw[jj][1] * x1[t8 + jj]; }
;                 *(LAS unsigned*)(lds + R_A_OFF + tt * 256 + (((cp >> 2) ^ (tt & 15)) << 4) + (cp & 3) * 4) = cvt_pk_bf16(y0, y1);
;             }
;         }
;         __syncthreads();
;         if (has_next) RNN_DMA(q + cnt);
;         float Pc[2] = {1.f, 1.f}, Hc[2] = {0.f, 0.f};
;         f2 hkeep[2][4];
;         LAS bf16* const stH = (LAS bf16*)(lds + R_ST_OFF) + (4 * fq) * 128 + nl;
;     ...
;                 LAS unsigned char* const stP = lds + R_ST_OFF + (dir == 0 ? 16384 : 32768) + (4 * fq) * 128 + nl;
;                 f2 Po[4], Ho[4];
; #pragma unroll
;                 for (int r = 0; r < 4; ++r) { Po[r] = Ps255 * p[dir][r]; Ho[r] = p[dir][r] * Hs + h[dir][r]; }
;                 { LAS unsigned char* sp_ = stP + (16 * m0) * 128;
; #pragma unroll
;                   for (int r = 0; r < 4; ++r) sp_[128 * r] = (unsigned char)__builtin_amdgcn_cvt_pk_u8_f32(Po[r].x, 0u, 0u); }
;                 { LAS unsigned char* sp_ = stP + (16 * m1) * 128;
; #pragma unroll
;                   for (int r = 0; r < 4; ++r) sp_[128 * r] = (unsigned char)__builtin_amdgcn_cvt_pk_u8_f32(Po[r].y, 0u, 0u); }
	v_bitop3_b32 v66, v65, s20, 8 bitop3:0x78
	v_lshl_add_u64 v[178:179], s[6:7], 0, v[88:89]
	v_lshl_add_u32 v89, v66, 4, s2
	s_or_b32 s2, s20, 1
	s_lshl_b32 s6, s2, 8
	s_add_i32 s6, s6, 0
	v_bitop3_b32 v66, v65, s2, 9 bitop3:0x78
	s_or_b32 s2, s20, 2
	v_lshl_add_u32 v97, v66, 4, s6
	s_lshl_b32 s6, s2, 8
	s_add_i32 s6, s6, 0
	v_bitop3_b32 v66, v65, s2, 10 bitop3:0x78
	s_or_b32 s2, s20, 3
	v_lshl_add_u32 v98, v66, 4, s6
	s_lshl_b32 s6, s2, 8
	s_add_i32 s6, s6, 0
	v_bitop3_b32 v66, v65, s2, 11 bitop3:0x78
	s_or_b32 s2, s20, 4
	v_lshl_add_u32 v99, v66, 4, s6
	s_lshl_b32 s6, s2, 8
	s_add_i32 s6, s6, 0
	v_bitop3_b32 v66, v65, s2, 12 bitop3:0x78
	s_or_b32 s2, s20, 5
	v_lshl_add_u32 v100, v66, 4, s6
	s_lshl_b32 s6, s2, 8
	s_add_i32 s6, s6, 0
	v_bitop3_b32 v66, v65, s2, 13 bitop3:0x78
	s_or_b32 s2, s20, 6
	v_lshl_add_u32 v101, v66, 4, s6
	s_lshl_b32 s6, s2, 8
	s_add_i32 s6, s6, 0
	v_bitop3_b32 v66, v65, s2, 14 bitop3:0x78
	s_or_b32 s2, s20, 7
	v_lshlrev_b32_e32 v71, 9, v86
	v_lshl_add_u32 v74, v86, 10, 0
	v_add_u32_e32 v75, s18, v86
	s_mov_b32 s18, 0x5040100
	v_lshl_add_u32 v102, v66, 4, s6
	s_lshl_b32 s6, s2, 8
	v_lshl_add_u32 v206, v84, 1, v74
	v_perm_b32 v82, v85, v82, s18
	v_sub_u32_e32 v85, v74, v71
	s_add_i32 s6, s6, 0
	v_xor_b32_e32 v74, v86, v73
	v_bitop3_b32 v65, v65, s2, 15 bitop3:0x78
	s_cmpk_lt_u32 s48, 0x440
	v_lshlrev_b32_e32 v104, 4, v74
	v_add_u32_e32 v74, 4, v86
	v_lshl_add_u32 v103, v65, 4, s6
	s_cselect_b64 s[6:7], -1, 0
	s_lshl_b32 s2, s21, 2
	s_lshl_b32 s22, s21, 10
	v_xor_b32_e32 v74, v74, v73
	v_ashrrev_i32_e32 v95, 3, v90
	s_cmpk_lt_u32 s48, 0x240
	v_lshlrev_b32_e32 v105, 4, v74
	v_add_u32_e32 v74, 8, v86
	v_ashrrev_i32_e32 v108, 4, v90
	v_add_u32_e32 v90, 0x200, v90
	v_cmp_eq_u32_e32 vcc, 1, v86
	s_cselect_b64 s[14:15], -1, 0
	v_xor_b32_e32 v74, v74, v73
	v_ashrrev_i32_e32 v90, 4, v90
	s_lshl_b32 s20, s8, 6
	v_cndmask_b32_e64 v166, 0, 1.0, vcc
	v_cmp_eq_u32_e32 vcc, 2, v86
	v_lshl_add_u32 v93, v73, 8, 0
	v_perm_b32 v83, v87, v83, s18
	v_perm_b32 v81, v81, v80, s18
	v_perm_b32 v80, v79, v69, s18
	s_movk_i32 s18, 0xff10
	v_lshlrev_b32_e32 v106, 4, v74
	v_add_u32_e32 v74, 12, v86
	v_add_u32_e32 v207, s20, v95
	v_add_u32_e32 v208, s20, v90
	v_add_u32_e32 v209, s20, v108
	s_add_i32 s20, s8, s13
	v_cmp_gt_u32_e64 s[0:1], 16, v70
	v_cndmask_b32_e64 v168, 0, 1.0, vcc
	v_cmp_eq_u32_e32 vcc, 3, v86
	v_xor_b32_e32 v75, v75, v73
	v_mad_i32_i24 v87, v73, s18, v93
	s_add_i32 s18, s22, 0x2000
	s_add_i32 s19, s22, 0x4000
	v_xor_b32_e32 v73, v74, v73
	s_lshl_b32 s20, s20, 6
	v_cndmask_b32_e64 v164, 0, 1.0, s[0:1]
	v_cndmask_b32_e64 v170, 0, 1.0, vcc
	v_lshlrev_b32_e32 v94, 4, v75
	v_lshl_add_u32 v96, v95, 7, 0
	v_lshlrev_b32_e32 v107, 4, v73
	v_lshlrev_b32_e32 v109, 8, v108
	v_lshlrev_b32_e32 v110, 8, v90
	s_add_i32 s2, s2, s20
	s_add_i32 s25, s18, 0
	s_add_i32 s26, s19, 0
	v_mov_b32_e32 v65, v64
	v_mov_b32_e32 v66, v64
	v_mov_b32_e32 v67, v64
	v_mov_b32_e32 v69, v68
	v_mov_b32_e32 v70, v68
	v_mov_b32_e32 v71, v68
	v_mov_b32_e32 v73, v72
	v_mov_b32_e32 v74, v72
	v_mov_b32_e32 v75, v72
	v_mov_b32_e32 v77, v76
	v_mov_b32_e32 v78, v76
	v_mov_b32_e32 v79, v76
	v_mov_b32_e32 v163, v162
	v_mov_b32_e32 v171, v170
	v_mov_b32_e32 v169, v168
	v_mov_b32_e32 v167, v166
	v_mov_b32_e32 v165, v164
	s_lshl_b32 s23, s13, 6
	v_add_u32_e32 v210, s2, v86
	v_add_u32_e32 v211, s16, v91
	v_add_u32_e32 v212, v89, v92
	v_add_u32_e32 v213, v97, v92
	v_add_u32_e32 v214, v98, v92
	v_add_u32_e32 v215, v99, v92
	v_add_u32_e32 v216, v100, v92
	v_add_u32_e32 v217, v101, v92
	v_add_u32_e32 v218, v102, v92
	v_add_u32_e32 v219, v103, v92
	s_movk_i32 s24, 0xa00
	s_add_i32 s25, s25, 0x10000
	s_add_i32 s26, s26, 0x10000
	v_add_u32_e32 v220, v93, v94
	v_add_u32_e32 v221, v93, v104
	v_add_u32_e32 v222, v93, v105
	v_add_u32_e32 v223, v93, v106
	v_add_u32_e32 v224, v93, v107
	s_mov_b32 s16, 0x437f0000
	v_add_u32_e32 v225, v85, v84
	v_add_u32_e32 v226, v87, v109
	v_add_u32_e32 v227, v87, v110
	s_movk_i32 s27, 0x500
	v_add_u32_e32 v228, v96, v88
	v_mov_b32_e32 v229, 0x3fff
	v_mov_b32_e32 v180, 1.0
	v_mbcnt_lo_u32_b32 v253, -1, 0
	v_mbcnt_hi_u32_b32 v253, -1, v253
	v_and_b32_e32 v250, 3, v253
	v_mul_u32_u24_e32 v250, 0x7f, v250
	v_add_u32_e32 v250, v225, v250
	v_and_b32_e32 v251, 1, v253
	v_cmp_ne_u32_e64 s[100:101], 0, v251
	v_mov_b32_e32 v251, 0x6020400
	v_mov_b32_e32 v252, 0x3070105
	v_cndmask_b32_e64 v251, v251, v252, s[100:101]
	v_and_b32_e32 v252, 2, v253
	v_cmp_ne_u32_e64 s[100:101], 0, v252
	v_mov_b32_e32 v252, 0x5040100
	v_mov_b32_e32 v253, 0x3020706
	v_cndmask_b32_e64 v252, v252, v253, s[100:101]
	s_branch .LBB0_616

; #define LAS __attribute__((address_space(3)))
; __device__ __forceinline__ void rnn_local_phase(Frame& F, const XcdBarrier& gbar, const bool use_bar) {
;     ...
;             f32x4 accr[2][2], acci[2][2], accx[2][2];
; #pragma unroll
;             for (int dir = 0; dir < 2; ++dir)
; #pragma unroll
;                 for (int t2 = 0; t2 < 2; ++t2) {
;                     const int m = t2 == 0 ? RNN_M0(dir, pr) : RNN_M1(dir, pr);
;                     accr[dir][t2] = (f32x4){nba[dir], nba[dir], nba[dir], nba[dir]}; acci[dir][t2] = (f32x4){nbx[dir], nbx[dir], nbx[dir], nbx[dir]};
;                     const LAS unsigned char* arow = lds + R_A_OFF + (16 * m + fr) * 256;
;                     const bf16x8 afx = *(const LAS bf16x8*)(arow + (((4 * ksx + fq) ^ fr) << 4));
; #pragma unroll
;                     for (int ks = 0; ks < 4; ++ks) {
;                         const bf16x8 af = *(const LAS bf16x8*)(arow + (((4 * ks + fq) ^ fr) << 4));
;                         accr[dir][t2] = __builtin_amdgcn_mfma_f32_16x16x32_bf16(af, br[dir][ks], accr[dir][t2], 0, 0, 0);
;                         acci[dir][t2] = __builtin_amdgcn_mfma_f32_16x16x32_bf16(af, bi[dir][ks], acci[dir][t2], 0, 0, 0);
;                     }
;                     accx[dir][t2] = __builtin_amdgcn_mfma_f32_16x16x32_bf16(afx, idf, (f32x4){0.f, 0.f, 0.f, 0.f}, 0, 0, 0);
;                 }
;             f2 a[2][4], u[2][4];
; #pragma unroll
;             for (int r = 0; r < 4; ++r)
; #pragma unroll
;                 for (int dir = 0; dir < 2; ++dir) {
;                     const f2 xc = (f2){accx[dir][0][r], accx[dir][1][r]};
;                     const f2 zr = (f2){accr[dir][0][r], accr[dir][1][r]}, zi = (f2){acci[dir][0][r], acci[dir][1][r]};
;                     const f2 dr = (f2){__builtin_amdgcn_exp2f(zr.x), __builtin_amdgcn_exp2f(zr.y)} + 1.0f, di = (f2){__builtin_amdgcn_exp2f(zi.x), __builtin_amdgcn_exp2f(zi.y)} + 1.0f;
;                     const f2 rg = (f2){__builtin_amdgcn_rcpf(dr.x), __builtin_amdgcn_rcpf(dr.y)}, ig = (f2){__builtin_amdgcn_rcpf(di.x), __builtin_amdgcn_rcpf(di.y)};
;                     const f2 l2a = rg * kap[dir];
;                     const f2 av = (f2){__builtin_amdgcn_exp2f(l2a.x), __builtin_amdgcn_exp2f(l2a.y)};
;                     const f2 om = 1.0f - av * av;
;                     const f2 sq = (f2){__builtin_amdgcn_sqrtf(om.x), __builtin_amdgcn_sqrtf(om.y)};
.LBB0_623:
	ds_read_b128 v[92:95], v220
	ds_read_b128 v[84:87], v221
	ds_read_b128 v[96:99], v222
	s_waitcnt lgkmcnt(0)
	v_mfma_f32_16x16x32_bf16 v[92:95], v[92:95], v[80:83], 0
	v_mfma_f32_16x16x32_bf16 v[88:91], v[84:87], v[0:3], v[64:67]
	v_mfma_f32_16x16x32_bf16 v[84:87], v[84:87], v[8:11], v[68:71]
	v_mfma_f32_16x16x32_bf16 v[88:91], v[96:99], v[4:7], v[88:91]
	v_mfma_f32_16x16x32_bf16 v[84:87], v[96:99], v[12:15], v[84:87]
	ds_read_b128 v[96:99], v223
	s_waitcnt lgkmcnt(0)
	v_mfma_f32_16x16x32_bf16 v[88:91], v[96:99], v[16:19], v[88:91]
	v_mfma_f32_16x16x32_bf16 v[84:87], v[96:99], v[24:27], v[84:87]
	ds_read_b128 v[96:99], v224
	s_waitcnt lgkmcnt(0)
	v_mfma_f32_16x16x32_bf16 v[88:91], v[96:99], v[20:23], v[88:91]
	v_mfma_f32_16x16x32_bf16 v[84:87], v[96:99], v[28:31], v[84:87]
	ds_read_b128 v[96:99], v220 offset:4096
	ds_read_b128 v[100:103], v221 offset:4096
	ds_read_b128 v[108:111], v222 offset:4096
	s_waitcnt lgkmcnt(0)
	v_mfma_f32_16x16x32_bf16 v[104:107], v[100:103], v[0:3], v[64:67]
	s_nop 2
	v_exp_f32_e32 v136, v84
	v_exp_f32_e32 v84, v85
	v_mfma_f32_16x16x32_bf16 v[100:103], v[100:103], v[8:11], v[68:71]
	v_mfma_f32_16x16x32_bf16 v[104:107], v[108:111], v[4:7], v[104:107]
	v_mfma_f32_16x16x32_bf16 v[100:103], v[108:111], v[12:15], v[100:103]
	ds_read_b128 v[108:111], v223 offset:4096
	s_waitcnt lgkmcnt(0)
	v_mfma_f32_16x16x32_bf16 v[104:107], v[108:111], v[16:19], v[104:107]
	v_mfma_f32_16x16x32_bf16 v[100:103], v[108:111], v[24:27], v[100:103]
	ds_read_b128 v[108:111], v224 offset:4096
	s_waitcnt lgkmcnt(0)
	v_mfma_f32_16x16x32_bf16 v[124:127], v[108:111], v[20:23], v[104:107]
	v_mfma_f32_16x16x32_bf16 v[112:115], v[108:111], v[28:31], v[100:103]
	v_mfma_f32_16x16x32_bf16 v[108:111], v[96:99], v[80:83], 0
	s_nop 1
	ds_read_b128 v[104:107], v220 offset:12288
	ds_read_b128 v[96:99], v221 offset:12288
	ds_read_b128 v[116:119], v222 offset:12288
	s_nop 1
	v_exp_f32_e32 v137, v112
	s_waitcnt lgkmcnt(0)
	v_mfma_f32_16x16x32_bf16 v[100:103], v[96:99], v[32:35], v[72:75]
	v_add_f32_e64 v136, v136, 1.0
	v_add_f32_e64 v137, v137, 1.0
	v_exp_f32_e32 v85, v113
	v_rcp_f32_e32 v136, v136
	v_mfma_f32_16x16x32_bf16 v[96:99], v[96:99], v[40:43], v[76:79]
	v_rcp_f32_e32 v137, v137
	v_pk_add_f32 v[84:85], v[84:85], 1.0 op_sel_hi:[1,0]
	v_exp_f32_e32 v112, v86
	v_mfma_f32_16x16x32_bf16 v[100:103], v[116:119], v[36:39], v[100:103]
	v_exp_f32_e32 v113, v114
	v_exp_f32_e32 v86, v87
	v_exp_f32_e32 v87, v115
	v_mfma_f32_16x16x32_bf16 v[96:99], v[116:119], v[44:47], v[96:99]
	ds_read_b128 v[116:119], v223 offset:12288
	v_pk_add_f32 v[112:113], v[112:113], 1.0 op_sel_hi:[1,0]
	v_pk_add_f32 v[86:87], v[86:87], 1.0 op_sel_hi:[1,0]
	s_waitcnt lgkmcnt(0)
	v_mfma_f32_16x16x32_bf16 v[100:103], v[116:119], v[48:51], v[100:103]
	v_rcp_f32_e32 v86, v86
	v_rcp_f32_e32 v87, v87
	v_mfma_f32_16x16x32_bf16 v[96:99], v[116:119], v[56:59], v[96:99]
	ds_read_b128 v[116:119], v224 offset:12288
	s_waitcnt lgkmcnt(0)
	v_mfma_f32_16x16x32_bf16 v[100:103], v[116:119], v[52:55], v[100:103]
	v_mfma_f32_16x16x32_bf16 v[96:99], v[116:119], v[60:63], v[96:99]
	v_mfma_f32_16x16x32_bf16 v[116:119], v[104:107], v[80:83], 0
	ds_read_b128 v[104:107], v220 offset:8192
	ds_read_b128 v[120:123], v221 offset:8192
	ds_read_b128 v[132:135], v222 offset:8192
	s_waitcnt lgkmcnt(0)
	v_mfma_f32_16x16x32_bf16 v[128:131], v[120:123], v[32:35], v[72:75]
	s_nop 2
	v_mov_b32_e32 v140, v116
	v_mov_b32_e32 v116, v94
	v_mfma_f32_16x16x32_bf16 v[120:123], v[120:123], v[40:43], v[76:79]
	v_mfma_f32_16x16x32_bf16 v[128:131], v[132:135], v[36:39], v[128:131]
	v_mfma_f32_16x16x32_bf16 v[120:123], v[132:135], v[44:47], v[120:123]
	ds_read_b128 v[132:135], v223 offset:8192
	s_waitcnt lgkmcnt(0)
	v_mfma_f32_16x16x32_bf16 v[128:131], v[132:135], v[48:51], v[128:131]
	v_mfma_f32_16x16x32_bf16 v[120:123], v[132:135], v[56:59], v[120:123]
	ds_read_b128 v[132:135], v224 offset:8192
	s_waitcnt lgkmcnt(0)
	v_mfma_f32_16x16x32_bf16 v[128:131], v[132:135], v[52:55], v[128:131]
	v_mfma_f32_16x16x32_bf16 v[120:123], v[132:135], v[60:63], v[120:123]
	v_exp_f32_e32 v132, v88
	v_exp_f32_e32 v133, v124
	v_mov_b32_e32 v134, v92
	v_mov_b32_e32 v135, v108
	v_pk_mul_f32 v[134:135], v[134:135], v[136:137]
	v_pk_add_f32 v[132:133], v[132:133], 1.0 op_sel_hi:[1,0]
	v_mov_b32_e32 v108, v93
	v_rcp_f32_e32 v132, v132
	v_rcp_f32_e32 v133, v133
	v_rcp_f32_e32 v92, v84
	v_rcp_f32_e32 v93, v85
	v_mfma_f32_16x16x32_bf16 v[104:107], v[104:107], v[80:83], 0
	v_mul_f32_e64 v132, v160, v132
	v_mul_f32_e64 v133, v161, v133
	v_exp_f32_e32 v136, v100
	v_exp_f32_e32 v132, v132
	v_exp_f32_e32 v133, v133
	v_pk_mul_f32 v[92:93], v[108:109], v[92:93]
	v_exp_f32_e32 v137, v128
	v_exp_f32_e32 v100, v101
	v_pk_fma_f32 v[138:139], v[132:133], v[132:133], 1.0 op_sel_hi:[1,1,0] neg_lo:[1,0,0] neg_hi:[1,0,0]
	v_exp_f32_e32 v101, v129
	v_sqrt_f32_e32 v138, v138
	v_sqrt_f32_e32 v139, v139
	v_exp_f32_e32 v128, v98
	v_exp_f32_e32 v129, v122
	v_mov_b32_e32 v141, v104
	v_pk_mul_f32 v[134:135], v[134:135], v[138:139]
	v_exp_f32_e32 v138, v96
	v_exp_f32_e32 v96, v97
	v_exp_f32_e32 v97, v121
	v_mov_b32_e32 v104, v117
	v_exp_f32_e32 v139, v120
	v_rcp_f32_e32 v120, v112
	v_pk_add_f32 v[96:97], v[96:97], 1.0 op_sel_hi:[1,0]
	v_rcp_f32_e32 v121, v113
	v_rcp_f32_e32 v108, v96
	v_rcp_f32_e32 v109, v97
	v_pk_add_f32 v[128:129], v[128:129], 1.0 op_sel_hi:[1,0]
	v_mov_b32_e32 v117, v110
	v_rcp_f32_e32 v128, v128
	v_pk_mul_f32 v[104:105], v[104:105], v[108:109]
	v_exp_f32_e32 v108, v90
	v_exp_f32_e32 v90, v91
	v_exp_f32_e32 v91, v127
	v_rcp_f32_e32 v129, v129
	v_pk_mul_f32 v[116:117], v[116:117], v[120:121]
	v_mov_b32_e32 v120, v118
	v_pk_add_f32 v[90:91], v[90:91], 1.0 op_sel_hi:[1,0]
; __device__ __forceinline__ void rnn_local_phase(Frame& F, const XcdBarrier& gbar, const bool use_bar) {
;     ...
;                     const f2 xc = (f2){accx[dir][0][r], accx[dir][1][r]};
;                     const f2 zr = (f2){accr[dir][0][r], accr[dir][1][r]}, zi = (f2){acci[dir][0][r], acci[dir][1][r]};
;                     const f2 dr = (f2){__builtin_amdgcn_exp2f(zr.x), __builtin_amdgcn_exp2f(zr.y)} + 1.0f, di = (f2){__builtin_amdgcn_exp2f(zi.x), __builtin_amdgcn_exp2f(zi.y)} + 1.0f;
;                     const f2 rg = (f2){__builtin_amdgcn_rcpf(dr.x), __builtin_amdgcn_rcpf(dr.y)}, ig = (f2){__builtin_amdgcn_rcpf(di.x), __builtin_amdgcn_rcpf(di.y)};
;                     const f2 l2a = rg * kap[dir];
;                     const f2 av = (f2){__builtin_amdgcn_exp2f(l2a.x), __builtin_amdgcn_exp2f(l2a.y)};
;                     const f2 om = 1.0f - av * av;
;                     const f2 sq = (f2){__builtin_amdgcn_sqrtf(om.x), __builtin_amdgcn_sqrtf(om.y)};
;                     a[dir][r] = av; u[dir][r] = sq * (ig * xc);
;                 }
;             f2 p[2][4], h[2][4];
;             p[0][0] = a[0][0]; h[0][0] = u[0][0]; p[1][3] = a[1][3]; h[1][3] = u[1][3];
; #pragma unroll
;             for (int r = 1; r < 4; ++r) {
;                 p[0][r] = a[0][r] * p[0][r - 1]; h[0][r] = a[0][r] * h[0][r - 1] + u[0][r];
;                 p[1][3 - r] = a[1][3 - r] * p[1][4 - r]; h[1][3 - r] = a[1][3 - r] * h[1][4 - r] + u[1][3 - r];
;             }
;             f2 LA[2][4], LH[2][4];
; #pragma unroll
;             for (int dir = 0; dir < 2; ++dir) {
;                 const f2 Ag = dir == 0 ? p[0][3] : p[1][0], Hg = dir == 0 ? h[0][3] : h[1][0];
; #pragma unroll
;                 for (int k = 0; k < 4; ++k) { LA[dir][k] = (f2){0.f, 0.f}; LH[dir][k] = (f2){0.f, 0.f}; }
;     ...
;                 RNN_GATHER4(Ag.x, LA[dir], x); RNN_GATHER4(Ag.y, LA[dir], y); RNN_GATHER4(Hg.x, LH[dir], x); RNN_GATHER4(Hg.y, LH[dir], y);
;     ...
;             }
; #pragma unroll
;             for (int dir = 0; dir < 2; ++dir) {
;                 const int m0 = RNN_M0(dir, pr), m1 = RNN_M1(dir, pr);
;                 const f2 e1A = LA[dir][0], e1H = LH[dir][0];
;                 const f2 e2A = LA[dir][1] * e1A, e2H = LA[dir][1] * e1H + LH[dir][1];
;                 const f2 e3A = LA[dir][2] * e2A, e3H = LA[dir][2] * e2H + LH[dir][2];
	v_mov_b32_e32 v121, v106
	v_mov_b32_e32 v110, v95
	v_rcp_f32_e32 v90, v90
	v_rcp_f32_e32 v91, v91
	v_pk_mul_f32 v[120:121], v[120:121], v[128:129]
	v_pk_mul_f32 v[128:129], v[110:111], v[86:87]
	v_exp_f32_e32 v86, v103
	v_exp_f32_e32 v87, v131
	v_exp_f32_e32 v88, v89
	v_exp_f32_e32 v89, v125
	v_exp_f32_e32 v124, v102
	v_exp_f32_e32 v125, v130
	v_exp_f32_e32 v109, v126
	v_pk_mul_f32 v[90:91], v[160:161], v[90:91]
	v_pk_add_f32 v[86:87], v[86:87], 1.0 op_sel_hi:[1,0]
	v_exp_f32_e32 v114, v90
	v_exp_f32_e32 v115, v91
	v_pk_add_f32 v[88:89], v[88:89], 1.0 op_sel_hi:[1,0]
	v_rcp_f32_e32 v86, v86
	v_rcp_f32_e32 v87, v87
	v_rcp_f32_e32 v88, v88
	v_rcp_f32_e32 v89, v89
	v_pk_add_f32 v[124:125], v[124:125], 1.0 op_sel_hi:[1,0]
	v_pk_add_f32 v[108:109], v[108:109], 1.0 op_sel_hi:[1,0]
	v_rcp_f32_e32 v124, v124
	v_rcp_f32_e32 v125, v125
	v_pk_add_f32 v[100:101], v[100:101], 1.0 op_sel_hi:[1,0]
	v_rcp_f32_e32 v108, v108
	v_rcp_f32_e32 v109, v109
	v_pk_fma_f32 v[90:91], v[114:115], v[114:115], 1.0 op_sel_hi:[1,1,0] neg_lo:[1,0,0] neg_hi:[1,0,0]
	v_rcp_f32_e32 v100, v100
	v_rcp_f32_e32 v101, v101
	v_sqrt_f32_e32 v126, v90
	v_sqrt_f32_e32 v127, v91
	v_exp_f32_e32 v90, v99
	v_exp_f32_e32 v91, v123
	v_pk_mul_f32 v[86:87], v[162:163], v[86:87]
	v_pk_mul_f32 v[84:85], v[160:161], v[88:89]
	v_exp_f32_e32 v86, v86
	v_exp_f32_e32 v87, v87
	v_pk_add_f32 v[138:139], v[138:139], 1.0 op_sel_hi:[1,0]
	v_exp_f32_e32 v84, v84
	v_exp_f32_e32 v85, v85
	v_pk_mul_f32 v[124:125], v[162:163], v[124:125]
	v_rcp_f32_e32 v142, v138
	v_rcp_f32_e32 v143, v139
	v_pk_mul_f32 v[108:109], v[160:161], v[108:109]
	v_exp_f32_e32 v124, v124
	v_exp_f32_e32 v125, v125
	v_pk_mul_f32 v[96:97], v[162:163], v[100:101]
	v_exp_f32_e32 v108, v108
	v_exp_f32_e32 v109, v109
	v_pk_add_f32 v[90:91], v[90:91], 1.0 op_sel_hi:[1,0]
	v_exp_f32_e32 v96, v96
	v_exp_f32_e32 v97, v97
	v_rcp_f32_e32 v90, v90
	v_rcp_f32_e32 v91, v91
	v_pk_fma_f32 v[94:95], v[86:87], v[86:87], 1.0 op_sel_hi:[1,1,0] neg_lo:[1,0,0] neg_hi:[1,0,0]
	v_pk_fma_f32 v[88:89], v[84:85], v[84:85], 1.0 op_sel_hi:[1,1,0] neg_lo:[1,0,0] neg_hi:[1,0,0]
	v_sqrt_f32_e32 v94, v94
	v_sqrt_f32_e32 v95, v95
	v_pk_add_f32 v[136:137], v[136:137], 1.0 op_sel_hi:[1,0]
	v_pk_mul_f32 v[140:141], v[140:141], v[142:143]
	v_sqrt_f32_e32 v88, v88
	v_sqrt_f32_e32 v89, v89
	v_pk_fma_f32 v[142:143], v[124:125], v[124:125], 1.0 op_sel_hi:[1,1,0] neg_lo:[1,0,0] neg_hi:[1,0,0]
	v_rcp_f32_e32 v136, v136
	v_rcp_f32_e32 v137, v137
	v_pk_fma_f32 v[112:113], v[108:109], v[108:109], 1.0 op_sel_hi:[1,1,0] neg_lo:[1,0,0] neg_hi:[1,0,0]
	v_sqrt_f32_e32 v142, v142
	v_sqrt_f32_e32 v143, v143
	v_mov_b32_e32 v106, v119
	v_pk_fma_f32 v[100:101], v[96:97], v[96:97], 1.0 op_sel_hi:[1,1,0] neg_lo:[1,0,0] neg_hi:[1,0,0]
	v_sqrt_f32_e32 v112, v112
	v_sqrt_f32_e32 v113, v113
	v_pk_mul_f32 v[90:91], v[106:107], v[90:91]
	v_sqrt_f32_e32 v100, v100
	v_sqrt_f32_e32 v101, v101
	v_pk_mul_f32 v[90:91], v[90:91], v[94:95]
	v_pk_mul_f32 v[102:103], v[84:85], v[132:133]
	v_pk_mul_f32 v[84:85], v[84:85], v[134:135]
	v_pk_mul_f32 v[136:137], v[162:163], v[136:137]
	v_pk_fma_f32 v[106:107], v[92:93], v[88:89], v[84:85]
	v_pk_mul_f32 v[88:89], v[124:125], v[90:91]
	v_pk_mul_f32 v[92:93], v[108:109], v[106:107]
	v_pk_fma_f32 v[88:89], v[120:121], v[142:143], v[88:89]
	v_exp_f32_e32 v136, v136
	v_exp_f32_e32 v137, v137
	v_pk_mul_f32 v[84:85], v[124:125], v[86:87]
	v_pk_mul_f32 v[110:111], v[108:109], v[102:103]
	v_pk_fma_f32 v[108:109], v[116:117], v[112:113], v[92:93]
	v_pk_mul_f32 v[94:95], v[96:97], v[88:89]
	v_pk_mul_f32 v[92:93], v[96:97], v[84:85]
	v_pk_fma_f32 v[94:95], v[104:105], v[100:101], v[94:95]
	v_pk_mul_f32 v[100:101], v[114:115], v[110:111]
	v_pk_mul_f32 v[96:97], v[114:115], v[108:109]
	v_mov_b32_e32 v112, v100
	v_pk_fma_f32 v[104:105], v[128:129], v[126:127], v[96:97]
	v_mov_b32_e32 v114, v100
	v_mov_b32_e32 v113, v101
	v_mov_b32_e32 v115, v101
	v_permlane16_swap_b32_e32 v112, v114
	s_nop 0
	v_permlane16_swap_b32_e32 v113, v115
	v_mov_b32_e32 v120, v104
	v_mov_b32_e32 v122, v104
	v_mov_b32_e32 v121, v105
	v_mov_b32_e32 v123, v105
	v_pk_fma_f32 v[138:139], v[136:137], v[136:137], 1.0 op_sel_hi:[1,1,0] neg_lo:[1,0,0] neg_hi:[1,0,0]
	v_mov_b32_e32 v116, v112
	v_mov_b32_e32 v118, v114
	v_mov_b32_e32 v117, v113
	v_mov_b32_e32 v119, v115
	v_permlane16_swap_b32_e32 v120, v122
	v_permlane16_swap_b32_e32 v121, v123
	v_sqrt_f32_e32 v138, v138
	v_sqrt_f32_e32 v139, v139
	v_permlane32_swap_b32_e32 v112, v116
	v_permlane32_swap_b32_e32 v114, v118
	v_permlane32_swap_b32_e32 v113, v117
	v_permlane32_swap_b32_e32 v115, v119
	v_mov_b32_e32 v124, v120
	v_mov_b32_e32 v126, v122
	v_mov_b32_e32 v125, v121
	v_mov_b32_e32 v127, v123
	v_permlane32_swap_b32_e32 v120, v124
	v_permlane32_swap_b32_e32 v122, v126
	v_permlane32_swap_b32_e32 v121, v125
	v_permlane32_swap_b32_e32 v123, v127
	v_pk_mul_f32 v[182:183], v[112:113], v[114:115]
	v_pk_mul_f32 v[96:97], v[136:137], v[92:93]
	v_pk_fma_f32 v[114:115], v[114:115], v[120:121], v[122:123]
	v_pk_mul_f32 v[122:123], v[182:183], v[116:117]
	v_pk_fma_f32 v[112:113], v[166:167], v[112:113], v[164:165]
	v_pk_mul_f32 v[98:99], v[136:137], v[94:95]
	v_mov_b32_e32 v128, v96
	v_mov_b32_e32 v130, v96
	v_mov_b32_e32 v129, v97
	v_mov_b32_e32 v131, v97
	v_pk_fma_f32 v[116:117], v[114:115], v[116:117], v[124:125]
	v_pk_mul_f32 v[124:125], v[122:123], v[118:119]
	v_pk_fma_f32 v[112:113], v[168:169], v[182:183], v[112:113]
	v_pk_mul_f32 v[114:115], v[168:169], v[114:115]
	v_pk_fma_f32 v[98:99], v[140:141], v[138:139], v[98:99]
	v_permlane16_swap_b32_e32 v128, v130
	v_permlane16_swap_b32_e32 v129, v131
	v_pk_fma_f32 v[190:191], v[116:117], v[118:119], v[126:127]
; #define LAS __attribute__((address_space(3)))
; __device__ __forceinline__ void rnn_local_phase(Frame& F, const XcdBarrier& gbar, const bool use_bar) {
;     ...
;                     const int m = t2 == 0 ? RNN_M0(dir, pr) : RNN_M1(dir, pr);
;                     accr[dir][t2] = (f32x4){nba[dir], nba[dir], nba[dir], nba[dir]}; acci[dir][t2] = (f32x4){nbx[dir], nbx[dir], nbx[dir], nbx[dir]};
;                     const LAS unsigned char* arow = lds + R_A_OFF + (16 * m + fr) * 256;
;                     const bf16x8 afx = *(const LAS bf16x8*)(arow + (((4 * ksx + fq) ^ fr) << 4));
; #pragma unroll
;                     for (int ks = 0; ks < 4; ++ks) {
;                         const bf16x8 af = *(const LAS bf16x8*)(arow + (((4 * ks + fq) ^ fr) << 4));
;     ...
;                 const f2 Ps = (f2){Pc[dir], Pc1} * Ae, Hs = Ae * (f2){Hc[dir], Hc1} + He; const f2 Ps255 = Ps * 255.0f;
;                 Pc[dir] = Pc1 * tA.y; Hc[dir] = tA.y * Hc1 + tH.y;
;                 LAS unsigned char* const stP = lds + R_ST_OFF + (dir == 0 ? 16384 : 32768) + (4 * fq) * 128 + nl;
;                 f2 Po[4], Ho[4];
; #pragma unroll
;                 for (int r = 0; r < 4; ++r) { Po[r] = Ps255 * p[dir][r]; Ho[r] = p[dir][r] * Hs + h[dir][r]; }
;                 { LAS unsigned char* sp_ = stP + (16 * m0) * 128;
; #pragma unroll
;                   for (int r = 0; r < 4; ++r) sp_[128 * r] = (unsigned char)__builtin_amdgcn_cvt_pk_u8_f32(Po[r].x, 0u, 0u); }
;                 { LAS unsigned char* sp_ = stP + (16 * m1) * 128;
; #pragma unroll
;                   for (int r = 0; r < 4; ++r) sp_[128 * r] = (unsigned char)__builtin_amdgcn_cvt_pk_u8_f32(Po[r].y, 0u, 0u); }
;                 if (pr == 0) {
; #pragma unroll
;                     for (int r = 0; r < 4; ++r) hkeep[dir][r] = Ho[r];
	v_pk_fma_f32 v[112:113], v[170:171], v[122:123], v[112:113]
	v_mov_b32_e32 v181, v124
	v_pk_fma_f32 v[114:115], v[166:167], v[120:121], v[114:115]
	v_mov_b32_e32 v136, v128
	v_mov_b32_e32 v138, v130
	v_mov_b32_e32 v137, v129
	v_mov_b32_e32 v139, v131
	v_mov_b32_e32 v140, v98
	v_mov_b32_e32 v142, v98
	v_mov_b32_e32 v141, v99
	v_mov_b32_e32 v143, v99
	v_fma_f32 v173, 0, v124, v190
	v_pk_mul_f32 v[118:119], v[112:113], v[180:181]
	v_pk_fma_f32 v[114:115], v[170:171], v[116:117], v[114:115]
	v_permlane32_swap_b32_e32 v128, v136
	v_permlane32_swap_b32_e32 v130, v138
	v_permlane32_swap_b32_e32 v129, v137
	v_permlane32_swap_b32_e32 v131, v139
	v_permlane16_swap_b32_e32 v140, v142
	v_permlane16_swap_b32_e32 v141, v143
	v_pk_mul_f32 v[118:119], v[118:119], s[16:17] op_sel_hi:[1,0]
	v_pk_fma_f32 v[112:113], v[112:113], v[172:173], v[114:115]
	v_mov_b32_e32 v144, v140
	v_mov_b32_e32 v146, v142
	v_mov_b32_e32 v145, v141
	v_mov_b32_e32 v147, v143
	v_pk_mul_f32 v[194:195], v[124:125], v[124:125] op_sel:[1,0] op_sel_hi:[0,1]
	v_fmac_f32_e32 v191, v125, v173
	v_pk_mul_f32 v[122:123], v[132:133], v[118:119]
	v_pk_mul_f32 v[124:125], v[102:103], v[118:119]
	v_pk_mul_f32 v[126:127], v[110:111], v[118:119]
	v_pk_mul_f32 v[118:119], v[100:101], v[118:119]
	v_pk_fma_f32 v[182:183], v[100:101], v[112:113], v[104:105]
	v_pk_mul_f32 v[100:101], v[136:137], v[138:139]
	v_permlane32_swap_b32_e32 v140, v144
	v_permlane32_swap_b32_e32 v142, v146
	v_permlane32_swap_b32_e32 v141, v145
	v_permlane32_swap_b32_e32 v143, v147
	v_pk_fma_f32 v[184:185], v[110:111], v[112:113], v[108:109]
	v_pk_mul_f32 v[104:105], v[100:101], v[130:131]
	v_pk_fma_f32 v[110:111], v[168:169], v[138:139], v[170:171]
	v_pk_fma_f32 v[186:187], v[102:103], v[112:113], v[106:107]
	v_pk_fma_f32 v[102:103], v[136:137], v[146:147], v[144:145]
	v_pk_mul_f32 v[108:109], v[104:105], v[128:129]
	v_pk_fma_f32 v[100:101], v[166:167], v[100:101], v[110:111]
	v_pk_fma_f32 v[106:107], v[102:103], v[130:131], v[142:143]
	v_pk_fma_f32 v[100:101], v[164:165], v[104:105], v[100:101]
	v_mov_b32_e32 v181, v108
	v_pk_fma_f32 v[192:193], v[106:107], v[128:129], v[140:141]
	v_pk_mul_f32 v[104:105], v[100:101], v[180:181]
	v_fma_f32 v173, 0, v108, v192
	v_pk_mul_f32 v[104:105], v[104:105], s[16:17] op_sel_hi:[1,0]
	v_pk_fma_f32 v[188:189], v[132:133], v[112:113], v[134:135]
	v_pk_mul_f32 v[196:197], v[108:109], v[108:109] op_sel:[1,0] op_sel_hi:[0,1]
	v_fmac_f32_e32 v193, v109, v173
	v_pk_mul_f32 v[108:109], v[96:97], v[104:105]
	v_pk_mul_f32 v[110:111], v[92:93], v[104:105]
	v_pk_mul_f32 v[112:113], v[84:85], v[104:105]
	v_pk_mul_f32 v[104:105], v[86:87], v[104:105]
	v_cvt_pk_u8_f32 v122, v122, 0, 0
	v_cvt_pk_u8_f32 v108, v108, 0, 0
	v_cvt_pk_u8_f32 v122, v124, 1, v122
	v_cvt_pk_u8_f32 v108, v110, 1, v108
	v_cvt_pk_u8_f32 v122, v126, 2, v122
	v_cvt_pk_u8_f32 v108, v112, 2, v108
	v_cvt_pk_u8_f32 v122, v118, 3, v122
	v_cvt_pk_u8_f32 v108, v104, 3, v108
	v_cvt_pk_u8_f32 v118, v123, 0, 0
	v_cvt_pk_u8_f32 v104, v109, 0, 0
	v_cvt_pk_u8_f32 v118, v125, 1, v118
	v_cvt_pk_u8_f32 v104, v111, 1, v104
	v_cvt_pk_u8_f32 v118, v127, 2, v118
	v_cvt_pk_u8_f32 v104, v113, 2, v104
	v_cvt_pk_u8_f32 v118, v119, 3, v118
	v_cvt_pk_u8_f32 v104, v105, 3, v104
	v_pk_mul_f32 v[102:103], v[166:167], v[102:103]
	v_mov_b32_dpp v253, v122 quad_perm:[1,0,3,2] row_mask:0xf bank_mask:0xf
	v_perm_b32 v122, v253, v122, v251
	v_mov_b32_dpp v253, v108 quad_perm:[1,0,3,2] row_mask:0xf bank_mask:0xf
	v_perm_b32 v108, v253, v108, v251
	v_mov_b32_dpp v253, v118 quad_perm:[1,0,3,2] row_mask:0xf bank_mask:0xf
	v_perm_b32 v118, v253, v118, v251
	v_mov_b32_dpp v253, v104 quad_perm:[1,0,3,2] row_mask:0xf bank_mask:0xf
	v_perm_b32 v104, v253, v104, v251
	v_pk_fma_f32 v[102:103], v[168:169], v[146:147], v[102:103]
	v_mov_b32_dpp v253, v122 quad_perm:[2,3,0,1] row_mask:0xf bank_mask:0xf
	v_perm_b32 v122, v253, v122, v252
	ds_write_b32 v250, v122 offset:32768
	v_mov_b32_dpp v253, v108 quad_perm:[2,3,0,1] row_mask:0xf bank_mask:0xf
	v_perm_b32 v108, v253, v108, v252
	ds_write_b32 v250, v108 offset:55296
	v_mov_b32_dpp v253, v118 quad_perm:[2,3,0,1] row_mask:0xf bank_mask:0xf
	v_perm_b32 v118, v253, v118, v252
	ds_write_b32 v250, v118 offset:34816
	v_mov_b32_dpp v253, v104 quad_perm:[2,3,0,1] row_mask:0xf bank_mask:0xf
	v_perm_b32 v104, v253, v104, v252
	ds_write_b32 v250, v104 offset:53248
	v_pk_fma_f32 v[102:103], v[164:165], v[106:107], v[102:103]
	v_pk_fma_f32 v[100:101], v[100:101], v[172:173], v[102:103]
	s_nop 0
	v_pk_fma_f32 v[198:199], v[86:87], v[100:101], v[90:91]
	v_pk_fma_f32 v[200:201], v[84:85], v[100:101], v[88:89]
	v_pk_fma_f32 v[202:203], v[92:93], v[100:101], v[94:95]
	v_pk_fma_f32 v[204:205], v[96:97], v[100:101], v[98:99]
	ds_read_b128 v[116:119], v224
	ds_read_b128 v[124:127], v223
	ds_read_b128 v[128:131], v222
	ds_read_b128 v[136:139], v221
	ds_read_b128 v[132:135], v220
	ds_read_b128 v[108:111], v224 offset:4096
	ds_read_b128 v[112:115], v223 offset:4096
	ds_read_b128 v[140:143], v222 offset:4096
	ds_read_b128 v[144:147], v221 offset:4096
	ds_read_b128 v[120:123], v220 offset:4096
	ds_read_b128 v[96:99], v224 offset:12288
	ds_read_b128 v[100:103], v223 offset:12288
	ds_read_b128 v[104:107], v222 offset:12288
	ds_read_b128 v[230:233], v221 offset:12288
	ds_read_b128 v[234:237], v220 offset:12288
	ds_read_b128 v[84:87], v224 offset:8192
	ds_read_b128 v[88:91], v223 offset:8192
	ds_read_b128 v[92:95], v222 offset:8192
	ds_read_b128 v[238:241], v221 offset:8192
	ds_read_b128 v[242:245], v220 offset:8192
	s_waitcnt lgkmcnt(0)
; #define LAS __attribute__((address_space(3)))
; __device__ __forceinline__ void rnn_local_phase(Frame& F, const XcdBarrier& gbar, const bool use_bar) {
;     ...
;             f32x4 accr[2][2], acci[2][2], accx[2][2];
; #pragma unroll
;             for (int dir = 0; dir < 2; ++dir)
; #pragma unroll
;                 for (int t2 = 0; t2 < 2; ++t2) {
;                     const int m = t2 == 0 ? RNN_M0(dir, pr) : RNN_M1(dir, pr);
;                     accr[dir][t2] = (f32x4){nba[dir], nba[dir], nba[dir], nba[dir]}; acci[dir][t2] = (f32x4){nbx[dir], nbx[dir], nbx[dir], nbx[dir]};
;                     const LAS unsigned char* arow = lds + R_A_OFF + (16 * m + fr) * 256;
;                     const bf16x8 afx = *(const LAS bf16x8*)(arow + (((4 * ksx + fq) ^ fr) << 4));
; #pragma unroll
;                     for (int ks = 0; ks < 4; ++ks) {
;                         const bf16x8 af = *(const LAS bf16x8*)(arow + (((4 * ks + fq) ^ fr) << 4));
;                         accr[dir][t2] = __builtin_amdgcn_mfma_f32_16x16x32_bf16(af, br[dir][ks], accr[dir][t2], 0, 0, 0);
;                         acci[dir][t2] = __builtin_amdgcn_mfma_f32_16x16x32_bf16(af, bi[dir][ks], acci[dir][t2], 0, 0, 0);
;                     }
;                     accx[dir][t2] = __builtin_amdgcn_mfma_f32_16x16x32_bf16(afx, idf, (f32x4){0.f, 0.f, 0.f, 0.f}, 0, 0, 0);
;                 }
;             f2 a[2][4], u[2][4];
; #pragma unroll
;             for (int r = 0; r < 4; ++r)
; #pragma unroll
;                 for (int dir = 0; dir < 2; ++dir) {
;                     const f2 xc = (f2){accx[dir][0][r], accx[dir][1][r]};
;                     const f2 zr = (f2){accr[dir][0][r], accr[dir][1][r]}, zi = (f2){acci[dir][0][r], acci[dir][1][r]};
;                     const f2 dr = (f2){__builtin_amdgcn_exp2f(zr.x), __builtin_amdgcn_exp2f(zr.y)} + 1.0f, di = (f2){__builtin_amdgcn_exp2f(zi.x), __builtin_amdgcn_exp2f(zi.y)} + 1.0f;
;                     const f2 rg = (f2){__builtin_amdgcn_rcpf(dr.x), __builtin_amdgcn_rcpf(dr.y)}, ig = (f2){__builtin_amdgcn_rcpf(di.x), __builtin_amdgcn_rcpf(di.y)};
;                     const f2 l2a = rg * kap[dir];
;                     const f2 av = (f2){__builtin_amdgcn_exp2f(l2a.x), __builtin_amdgcn_exp2f(l2a.y)};
;                     const f2 om = 1.0f - av * av;
;                     const f2 sq = (f2){__builtin_amdgcn_sqrtf(om.x), __builtin_amdgcn_sqrtf(om.y)};
	v_mfma_f32_16x16x32_bf16 v[246:249], v[238:241], v[0:3], v[64:67]
	v_mfma_f32_16x16x32_bf16 v[238:241], v[238:241], v[8:11], v[68:71]
	v_mfma_f32_16x16x32_bf16 v[246:249], v[92:95], v[4:7], v[246:249]
	v_mfma_f32_16x16x32_bf16 v[92:95], v[92:95], v[12:15], v[238:241]
	v_mfma_f32_16x16x32_bf16 v[238:241], v[88:91], v[16:19], v[246:249]
	v_mfma_f32_16x16x32_bf16 v[92:95], v[88:91], v[24:27], v[92:95]
	v_mfma_f32_16x16x32_bf16 v[88:91], v[84:87], v[20:23], v[238:241]
	v_mfma_f32_16x16x32_bf16 v[238:241], v[230:233], v[0:3], v[64:67]
	v_mfma_f32_16x16x32_bf16 v[230:233], v[230:233], v[8:11], v[68:71]
	v_mfma_f32_16x16x32_bf16 v[238:241], v[104:107], v[4:7], v[238:241]
	v_mfma_f32_16x16x32_bf16 v[104:107], v[104:107], v[12:15], v[230:233]
	v_mfma_f32_16x16x32_bf16 v[230:233], v[100:103], v[16:19], v[238:241]
	v_mfma_f32_16x16x32_bf16 v[100:103], v[100:103], v[24:27], v[104:107]
	v_mfma_f32_16x16x32_bf16 v[104:107], v[96:99], v[20:23], v[230:233]
	v_mfma_f32_16x16x32_bf16 v[230:233], v[144:147], v[32:35], v[72:75]
	v_mfma_f32_16x16x32_bf16 v[144:147], v[144:147], v[40:43], v[76:79]
	v_mfma_f32_16x16x32_bf16 v[230:233], v[140:143], v[36:39], v[230:233]
	v_mfma_f32_16x16x32_bf16 v[140:143], v[140:143], v[44:47], v[144:147]
	v_mfma_f32_16x16x32_bf16 v[144:147], v[112:115], v[48:51], v[230:233]
	v_mfma_f32_16x16x32_bf16 v[140:143], v[112:115], v[56:59], v[140:143]
	v_mfma_f32_16x16x32_bf16 v[112:115], v[108:111], v[52:55], v[144:147]
	v_mfma_f32_16x16x32_bf16 v[108:111], v[108:111], v[60:63], v[140:143]
	v_mfma_f32_16x16x32_bf16 v[140:143], v[136:139], v[32:35], v[72:75]
	v_mfma_f32_16x16x32_bf16 v[136:139], v[136:139], v[40:43], v[76:79]
	v_mfma_f32_16x16x32_bf16 v[140:143], v[128:131], v[36:39], v[140:143]
	v_mfma_f32_16x16x32_bf16 v[128:131], v[128:131], v[44:47], v[136:139]
	v_mfma_f32_16x16x32_bf16 v[84:87], v[84:87], v[28:31], v[92:95]
	v_mfma_f32_16x16x32_bf16 v[100:103], v[96:99], v[28:31], v[100:103]
	v_mfma_f32_16x16x32_bf16 v[136:139], v[124:127], v[48:51], v[140:143]
	v_mfma_f32_16x16x32_bf16 v[124:127], v[124:127], v[56:59], v[128:131]
	v_mfma_f32_16x16x32_bf16 v[128:131], v[116:119], v[52:55], v[136:139]
	s_nop 5
	v_exp_f32_e32 v136, v84
	v_exp_f32_e32 v137, v100
	v_mfma_f32_16x16x32_bf16 v[124:127], v[116:119], v[60:63], v[124:127]
	v_exp_f32_e32 v84, v85
	v_exp_f32_e32 v85, v101
	v_pk_add_f32 v[136:137], v[136:137], 1.0 op_sel_hi:[1,0]
	v_mfma_f32_16x16x32_bf16 v[116:119], v[132:135], v[80:83], 0
	v_exp_f32_e32 v132, v88
	v_exp_f32_e32 v133, v104
	v_rcp_f32_e32 v136, v136
	v_mfma_f32_16x16x32_bf16 v[92:95], v[242:245], v[80:83], 0
	v_rcp_f32_e32 v137, v137
	v_pk_add_f32 v[132:133], v[132:133], 1.0 op_sel_hi:[1,0]
	v_exp_f32_e32 v100, v109
	v_mfma_f32_16x16x32_bf16 v[96:99], v[234:237], v[80:83], 0
	v_rcp_f32_e32 v132, v132
	v_rcp_f32_e32 v133, v133
	s_nop 1
	v_mov_b32_e32 v134, v92
	v_exp_f32_e32 v101, v125
	v_mfma_f32_16x16x32_bf16 v[120:123], v[120:123], v[80:83], 0
	s_nop 0
	v_mov_b32_e32 v135, v96
	v_pk_mul_f32 v[134:135], v[134:135], v[136:137]
	v_exp_f32_e32 v136, v112
	v_exp_f32_e32 v112, v86
	v_exp_f32_e32 v86, v87
	v_exp_f32_e32 v87, v103
	v_pk_mul_f32 v[132:133], v[160:161], v[132:133]
	v_pk_add_f32 v[100:101], v[100:101], 1.0 op_sel_hi:[1,0]
	v_exp_f32_e32 v132, v132
	v_exp_f32_e32 v133, v133
	v_exp_f32_e32 v88, v89
	v_exp_f32_e32 v89, v105
	v_rcp_f32_e32 v104, v100
	v_rcp_f32_e32 v105, v101
	v_pk_add_f32 v[86:87], v[86:87], 1.0 op_sel_hi:[1,0]
	v_pk_fma_f32 v[138:139], v[132:133], v[132:133], 1.0 op_sel_hi:[1,1,0] neg_lo:[1,0,0] neg_hi:[1,0,0]
	v_rcp_f32_e32 v86, v86
	v_rcp_f32_e32 v87, v87
	v_sqrt_f32_e32 v138, v138
	v_sqrt_f32_e32 v139, v139
	v_mov_b32_e32 v141, v116
	v_mov_b32_e32 v116, v121
	v_pk_add_f32 v[84:85], v[84:85], 1.0 op_sel_hi:[1,0]
	v_pk_mul_f32 v[104:105], v[116:117], v[104:105]
	v_mov_b32_e32 v117, v98
	v_mov_b32_e32 v98, v95
	v_mov_b32_e32 v96, v93
	v_rcp_f32_e32 v92, v84
	v_rcp_f32_e32 v93, v85
	v_pk_mul_f32 v[98:99], v[98:99], v[86:87]
	v_exp_f32_e32 v86, v115
	v_exp_f32_e32 v87, v131
	v_pk_mul_f32 v[134:135], v[134:135], v[138:139]
	v_exp_f32_e32 v139, v124
	v_exp_f32_e32 v124, v114
	v_exp_f32_e32 v125, v130
	v_exp_f32_e32 v138, v108
	v_exp_f32_e32 v108, v90
	v_exp_f32_e32 v109, v106
	v_pk_mul_f32 v[92:93], v[96:97], v[92:93]
	v_exp_f32_e32 v96, v113
	v_exp_f32_e32 v97, v129
	v_pk_add_f32 v[86:87], v[86:87], 1.0 op_sel_hi:[1,0]
	v_pk_add_f32 v[88:89], v[88:89], 1.0 op_sel_hi:[1,0]
	v_exp_f32_e32 v90, v91
	v_exp_f32_e32 v91, v107
	v_rcp_f32_e32 v86, v86
	v_rcp_f32_e32 v87, v87
	v_exp_f32_e32 v137, v128
	v_rcp_f32_e32 v88, v88
	v_rcp_f32_e32 v89, v89
	v_pk_add_f32 v[124:125], v[124:125], 1.0 op_sel_hi:[1,0]
	v_pk_add_f32 v[108:109], v[108:109], 1.0 op_sel_hi:[1,0]
	v_rcp_f32_e32 v124, v124
	v_rcp_f32_e32 v125, v125
	v_pk_add_f32 v[96:97], v[96:97], 1.0 op_sel_hi:[1,0]
	v_exp_f32_e32 v113, v102
	v_rcp_f32_e32 v108, v108
	v_rcp_f32_e32 v109, v109
	v_rcp_f32_e32 v96, v96
	v_rcp_f32_e32 v97, v97
	v_pk_add_f32 v[90:91], v[90:91], 1.0 op_sel_hi:[1,0]
	v_exp_f32_e32 v102, v111
	v_exp_f32_e32 v103, v127
	v_pk_mul_f32 v[86:87], v[162:163], v[86:87]
	v_pk_add_f32 v[136:137], v[136:137], 1.0 op_sel_hi:[1,0]
	v_pk_mul_f32 v[84:85], v[160:161], v[88:89]
	v_rcp_f32_e32 v90, v90
	v_rcp_f32_e32 v91, v91
	v_exp_f32_e32 v86, v86
	v_exp_f32_e32 v87, v87
	v_pk_add_f32 v[138:139], v[138:139], 1.0 op_sel_hi:[1,0]
	v_rcp_f32_e32 v136, v136
	v_rcp_f32_e32 v137, v137
	v_exp_f32_e32 v84, v84
	v_exp_f32_e32 v85, v85
	v_exp_f32_e32 v128, v110
	v_exp_f32_e32 v129, v126
	v_pk_mul_f32 v[124:125], v[162:163], v[124:125]
	v_rcp_f32_e32 v142, v138
	v_rcp_f32_e32 v143, v139
	v_pk_add_f32 v[112:113], v[112:113], 1.0 op_sel_hi:[1,0]
; __device__ __forceinline__ void rnn_local_phase(Frame& F, const XcdBarrier& gbar, const bool use_bar) {
;     ...
;             f2 p[2][4], h[2][4];
;             p[0][0] = a[0][0]; h[0][0] = u[0][0]; p[1][3] = a[1][3]; h[1][3] = u[1][3];
; #pragma unroll
;             for (int r = 1; r < 4; ++r) {
;                 p[0][r] = a[0][r] * p[0][r - 1]; h[0][r] = a[0][r] * h[0][r - 1] + u[0][r];
;                 p[1][3 - r] = a[1][3 - r] * p[1][4 - r]; h[1][3 - r] = a[1][3 - r] * h[1][4 - r] + u[1][3 - r];
;             }
;             f2 LA[2][4], LH[2][4];
; #pragma unroll
;             for (int dir = 0; dir < 2; ++dir) {
;                 const f2 Ag = dir == 0 ? p[0][3] : p[1][0], Hg = dir == 0 ? h[0][3] : h[1][0];
; #pragma unroll
;                 for (int k = 0; k < 4; ++k) { LA[dir][k] = (f2){0.f, 0.f}; LH[dir][k] = (f2){0.f, 0.f}; }
;     ...
;                 RNN_GATHER4(Ag.x, LA[dir], x); RNN_GATHER4(Ag.y, LA[dir], y); RNN_GATHER4(Hg.x, LH[dir], x); RNN_GATHER4(Hg.y, LH[dir], y);
;     ...
;             }
; #pragma unroll
;             for (int dir = 0; dir < 2; ++dir) {
;                 const int m0 = RNN_M0(dir, pr), m1 = RNN_M1(dir, pr);
;                 const f2 e1A = LA[dir][0], e1H = LH[dir][0];
;                 const f2 e2A = LA[dir][1] * e1A, e2H = LA[dir][1] * e1H + LH[dir][1];
;                 const f2 e3A = LA[dir][2] * e2A, e3H = LA[dir][2] * e2H + LH[dir][2];
;                 const f2 tA = LA[dir][3] * e3A, tH = LA[dir][3] * e3H + LH[dir][3];
;                 const float g0 = dir == 0 ? mk0 : mk3, g1 = dir == 0 ? mk1 : mk2, g2 = dir == 0 ? mk2 : mk1, g3 = dir == 0 ? mk3 : mk0;
;                 const f2 Ae = e3A * g3 + (e2A * g2 + (e1A * g1 + g0));
;                 const f2 He = e3H * g3 + (e2H * g2 + e1H * g1);
;                 const float Pc1 = Pc[dir] * tA.x, Hc1 = tA.x * Hc[dir] + tH.x;
;                 const f2 Ps = (f2){Pc[dir], Pc1} * Ae, Hs = Ae * (f2){Hc[dir], Hc1} + He; const f2 Ps255 = Ps * 255.0f;
;                 Pc[dir] = Pc1 * tA.y; Hc[dir] = tA.y * Hc1 + tH.y;
;                 LAS unsigned char* const stP = lds + R_ST_OFF + (dir == 0 ? 16384 : 32768) + (4 * fq) * 128 + nl;
;                 f2 Po[4], Ho[4];
; #pragma unroll
;                 for (int r = 0; r < 4; ++r) { Po[r] = Ps255 * p[dir][r]; Ho[r] = p[dir][r] * Hs + h[dir][r]; }
;                 { LAS unsigned char* sp_ = stP + (16 * m0) * 128;
; #pragma unroll
	v_pk_mul_f32 v[108:109], v[160:161], v[108:109]
	v_exp_f32_e32 v124, v124
	v_exp_f32_e32 v125, v125
	v_mov_b32_e32 v140, v120
	v_pk_mul_f32 v[96:97], v[162:163], v[96:97]
	v_rcp_f32_e32 v120, v112
	v_rcp_f32_e32 v121, v113
	v_exp_f32_e32 v108, v108
	v_exp_f32_e32 v109, v109
	v_pk_add_f32 v[102:103], v[102:103], 1.0 op_sel_hi:[1,0]
	v_exp_f32_e32 v96, v96
	v_exp_f32_e32 v97, v97
	v_pk_mul_f32 v[90:91], v[160:161], v[90:91]
	v_rcp_f32_e32 v102, v102
	v_rcp_f32_e32 v103, v103
	v_pk_fma_f32 v[106:107], v[86:87], v[86:87], 1.0 op_sel_hi:[1,1,0] neg_lo:[1,0,0] neg_hi:[1,0,0]
	v_pk_mul_f32 v[136:137], v[162:163], v[136:137]
	v_pk_fma_f32 v[88:89], v[84:85], v[84:85], 1.0 op_sel_hi:[1,1,0] neg_lo:[1,0,0] neg_hi:[1,0,0]
	v_pk_add_f32 v[128:129], v[128:129], 1.0 op_sel_hi:[1,0]
	v_exp_f32_e32 v90, v90
	v_exp_f32_e32 v91, v91
	v_sqrt_f32_e32 v106, v106
	v_sqrt_f32_e32 v107, v107
	v_exp_f32_e32 v136, v136
	v_exp_f32_e32 v137, v137
	v_pk_mul_f32 v[140:141], v[140:141], v[142:143]
	v_sqrt_f32_e32 v88, v88
	v_sqrt_f32_e32 v89, v89
	v_mov_b32_e32 v116, v94
	v_rcp_f32_e32 v128, v128
	v_rcp_f32_e32 v129, v129
	v_pk_fma_f32 v[142:143], v[124:125], v[124:125], 1.0 op_sel_hi:[1,1,0] neg_lo:[1,0,0] neg_hi:[1,0,0]
	v_pk_fma_f32 v[112:113], v[108:109], v[108:109], 1.0 op_sel_hi:[1,1,0] neg_lo:[1,0,0] neg_hi:[1,0,0]
	v_pk_mul_f32 v[116:117], v[116:117], v[120:121]
	v_mov_b32_e32 v121, v118
	v_sqrt_f32_e32 v142, v142
	v_sqrt_f32_e32 v143, v143
	v_mov_b32_e32 v118, v123
	v_pk_fma_f32 v[100:101], v[96:97], v[96:97], 1.0 op_sel_hi:[1,1,0] neg_lo:[1,0,0] neg_hi:[1,0,0]
	v_sqrt_f32_e32 v112, v112
	v_sqrt_f32_e32 v113, v113
	v_pk_mul_f32 v[102:103], v[118:119], v[102:103]
	v_sqrt_f32_e32 v100, v100
	v_sqrt_f32_e32 v101, v101
	v_mov_b32_e32 v120, v122
	v_pk_fma_f32 v[94:95], v[90:91], v[90:91], 1.0 op_sel_hi:[1,1,0] neg_lo:[1,0,0] neg_hi:[1,0,0]
	v_pk_mul_f32 v[102:103], v[102:103], v[106:107]
	v_pk_mul_f32 v[106:107], v[84:85], v[132:133]
	v_pk_mul_f32 v[84:85], v[84:85], v[134:135]
	v_pk_fma_f32 v[138:139], v[136:137], v[136:137], 1.0 op_sel_hi:[1,1,0] neg_lo:[1,0,0] neg_hi:[1,0,0]
	v_pk_mul_f32 v[120:121], v[120:121], v[128:129]
	v_sqrt_f32_e32 v94, v94
	v_sqrt_f32_e32 v95, v95
	v_pk_fma_f32 v[110:111], v[92:93], v[88:89], v[84:85]
	v_pk_mul_f32 v[84:85], v[124:125], v[102:103]
	v_sqrt_f32_e32 v138, v138
	v_sqrt_f32_e32 v139, v139
	v_pk_fma_f32 v[118:119], v[120:121], v[142:143], v[84:85]
	v_pk_mul_f32 v[84:85], v[108:109], v[110:111]
	v_pk_mul_f32 v[120:121], v[108:109], v[106:107]
	v_pk_fma_f32 v[108:109], v[116:117], v[112:113], v[84:85]
	v_pk_mul_f32 v[84:85], v[96:97], v[118:119]
	v_pk_mul_f32 v[114:115], v[124:125], v[86:87]
	v_pk_fma_f32 v[104:105], v[104:105], v[100:101], v[84:85]
	v_pk_mul_f32 v[84:85], v[90:91], v[108:109]
	v_pk_mul_f32 v[112:113], v[96:97], v[114:115]
	v_pk_mul_f32 v[96:97], v[90:91], v[120:121]
	v_pk_fma_f32 v[94:95], v[98:99], v[94:95], v[84:85]
	v_pk_mul_f32 v[84:85], v[136:137], v[104:105]
	v_mov_b32_e32 v90, v96
	v_pk_fma_f32 v[122:123], v[140:141], v[138:139], v[84:85]
	v_mov_b32_e32 v84, v96
	v_mov_b32_e32 v91, v97
	v_mov_b32_e32 v85, v97
	v_permlane16_swap_b32_e32 v90, v84
	s_nop 0
	v_permlane16_swap_b32_e32 v91, v85
	v_mov_b32_e32 v98, v94
	v_mov_b32_e32 v100, v94
	v_mov_b32_e32 v99, v95
	v_mov_b32_e32 v101, v95
	v_mov_b32_e32 v88, v90
	v_mov_b32_e32 v92, v84
	v_mov_b32_e32 v89, v91
	v_mov_b32_e32 v93, v85
	v_permlane16_swap_b32_e32 v98, v100
	v_permlane16_swap_b32_e32 v99, v101
	v_permlane32_swap_b32_e32 v90, v88
	v_permlane32_swap_b32_e32 v84, v92
	v_permlane32_swap_b32_e32 v91, v89
	v_permlane32_swap_b32_e32 v85, v93
	v_mov_b32_e32 v124, v98
	v_mov_b32_e32 v126, v100
	v_mov_b32_e32 v125, v99
	v_mov_b32_e32 v127, v101
	v_permlane32_swap_b32_e32 v98, v124
	v_permlane32_swap_b32_e32 v100, v126
	v_permlane32_swap_b32_e32 v99, v125
	v_permlane32_swap_b32_e32 v101, v127
	v_pk_mul_f32 v[230:231], v[90:91], v[84:85]
	v_pk_fma_f32 v[100:101], v[84:85], v[98:99], v[100:101]
	v_pk_mul_f32 v[232:233], v[230:231], v[88:89]
	v_pk_fma_f32 v[90:91], v[166:167], v[90:91], v[164:165]
	v_pk_fma_f32 v[124:125], v[100:101], v[88:89], v[124:125]
	v_pk_mul_f32 v[88:89], v[232:233], v[92:93]
	v_pk_fma_f32 v[90:91], v[168:169], v[230:231], v[90:91]
	v_pk_fma_f32 v[84:85], v[124:125], v[92:93], v[126:127]
	v_pk_fma_f32 v[126:127], v[170:171], v[232:233], v[90:91]
	v_pk_mul_f32 v[90:91], v[194:195], v[88:89]
	v_fma_f32 v93, v191, v88, v84
	v_mov_b32_e32 v195, v90
	v_pk_mul_f32 v[194:195], v[126:127], v[194:195]
	v_pk_mul_f32 v[100:101], v[168:169], v[100:101]
	v_pk_mul_f32 v[194:195], v[194:195], s[16:17] op_sel_hi:[1,0]
	v_pk_mul_f32 v[116:117], v[136:137], v[112:113]
	v_pk_mul_f32 v[230:231], v[132:133], v[194:195]
	v_pk_mul_f32 v[232:233], v[106:107], v[194:195]
	v_cvt_pk_u8_f32 v84, v230, 0, 0
	v_pk_mul_f32 v[234:235], v[120:121], v[194:195]
	v_cvt_pk_u8_f32 v84, v232, 1, v84
	v_pk_mul_f32 v[194:195], v[96:97], v[194:195]
	v_cvt_pk_u8_f32 v84, v234, 2, v84
	v_cvt_pk_u8_f32 v84, v194, 3, v84
	s_nop 1
	v_mov_b32_dpp v253, v84 quad_perm:[1,0,3,2] row_mask:0xf bank_mask:0xf
	v_perm_b32 v84, v253, v84, v251
	s_nop 1
	v_mov_b32_dpp v253, v84 quad_perm:[2,3,0,1] row_mask:0xf bank_mask:0xf
	v_perm_b32 v84, v253, v84, v252
	ds_write_b32 v250, v84 offset:36864
	v_cvt_pk_u8_f32 v84, v231, 0, 0
	v_pk_fma_f32 v[98:99], v[166:167], v[98:99], v[100:101]
	v_mov_b32_e32 v128, v116
	v_mov_b32_e32 v130, v116
	v_mov_b32_e32 v129, v117
	v_mov_b32_e32 v131, v117
	v_cvt_pk_u8_f32 v84, v233, 1, v84
	v_pk_fma_f32 v[98:99], v[170:171], v[124:125], v[98:99]
	v_mov_b32_e32 v92, v191
	v_permlane16_swap_b32_e32 v128, v130
	v_permlane16_swap_b32_e32 v129, v131
; __device__ __forceinline__ unsigned cvt_pk_bf16(float lo, float hi) { unsigned r; asm volatile("v_cvt_pk_bf16_f32 %0, %1, %2" : "=v"(r) : "v"(lo), "v"(hi)); return r; }
; #define LAS __attribute__((address_space(3)))
; __device__ __forceinline__ void rnn_local_phase(Frame& F, const XcdBarrier& gbar, const bool use_bar) {
;     ...
;                 LAS unsigned char* const stP = lds + R_ST_OFF + (dir == 0 ? 16384 : 32768) + (4 * fq) * 128 + nl;
;                 f2 Po[4], Ho[4];
; #pragma unroll
;                 for (int r = 0; r < 4; ++r) { Po[r] = Ps255 * p[dir][r]; Ho[r] = p[dir][r] * Hs + h[dir][r]; }
;                 { LAS unsigned char* sp_ = stP + (16 * m0) * 128;
; #pragma unroll
;                   for (int r = 0; r < 4; ++r) sp_[128 * r] = (unsigned char)__builtin_amdgcn_cvt_pk_u8_f32(Po[r].x, 0u, 0u); }
;                 { LAS unsigned char* sp_ = stP + (16 * m1) * 128;
; #pragma unroll
;                   for (int r = 0; r < 4; ++r) sp_[128 * r] = (unsigned char)__builtin_amdgcn_cvt_pk_u8_f32(Po[r].y, 0u, 0u); }
;                 if (pr == 0) {
; #pragma unroll
;                     for (int r = 0; r < 4; ++r) hkeep[dir][r] = Ho[r];
;                 } else {
;                     f2 hs[4];
; #pragma unroll
;                     for (int r = 0; r < 4; ++r) hs[r] = (f2){hkeep[1 - dir][r].y, hkeep[1 - dir][r].x} + Ho[r];
;                     { const unsigned h01 = cvt_pk_bf16(hs[0].x, hs[1].x), h23 = cvt_pk_bf16(hs[2].x, hs[3].x); LAS bf16* sh_ = stH + (16 * m0) * 128;
;                       sh_[0] = (bf16)(h01 & 0xffffu); sh_[128] = (bf16)(h01 >> 16); sh_[256] = (bf16)(h23 & 0xffffu); sh_[384] = (bf16)(h23 >> 16); }
;                     { const unsigned h01 = cvt_pk_bf16(hs[0].y, hs[1].y), h23 = cvt_pk_bf16(hs[2].y, hs[3].y); LAS bf16* sh_ = stH + (16 * m1) * 128;
;                       sh_[0] = (bf16)(h01 & 0xffffu); sh_[128] = (bf16)(h01 >> 16); sh_[256] = (bf16)(h23 & 0xffffu); sh_[384] = (bf16)(h23 >> 16); }
;                 }
;             }
;         }
;     ...
;         asm volatile("s_waitcnt vmcnt(0)" ::: "memory");
;         if (fq == 0) { AGG[((size_t)q * 2 + 0) * DRNN + c] = (f32x2){Pc[0], Hc[0]}; AGG[((size_t)q * 2 + 1) * DRNN + c] = (f32x2){Pc[1], Hc[1]}; }
	v_cvt_pk_u8_f32 v84, v235, 2, v84
	v_pk_fma_f32 v[98:99], v[126:127], v[92:93], v[98:99]
	v_mov_b32_e32 v136, v128
	v_mov_b32_e32 v138, v130
	v_mov_b32_e32 v137, v129
	v_mov_b32_e32 v139, v131
	v_cvt_pk_u8_f32 v84, v195, 3, v84
	v_pk_fma_f32 v[94:95], v[96:97], v[98:99], v[94:95]
	v_pk_fma_f32 v[96:97], v[120:121], v[98:99], v[108:109]
	v_pk_fma_f32 v[100:101], v[106:107], v[98:99], v[110:111]
	v_pk_fma_f32 v[98:99], v[132:133], v[98:99], v[134:135]
	v_permlane32_swap_b32_e32 v128, v136
	v_permlane32_swap_b32_e32 v130, v138
	v_permlane32_swap_b32_e32 v129, v137
	v_permlane32_swap_b32_e32 v131, v139
	s_nop 1
	v_mov_b32_dpp v253, v84 quad_perm:[1,0,3,2] row_mask:0xf bank_mask:0xf
	v_perm_b32 v84, v253, v84, v251
	s_nop 1
	v_mov_b32_dpp v253, v84 quad_perm:[2,3,0,1] row_mask:0xf bank_mask:0xf
	v_perm_b32 v84, v253, v84, v252
	ds_write_b32 v250, v84 offset:38912
	v_pk_add_f32 v[98:99], v[204:205], v[98:99] op_sel:[1,0] op_sel_hi:[0,1]
	v_pk_add_f32 v[100:101], v[202:203], v[100:101] op_sel:[1,0] op_sel_hi:[0,1]
	v_cvt_pk_bf16_f32 v84, v98, v100
	v_pk_add_f32 v[96:97], v[200:201], v[96:97] op_sel:[1,0] op_sel_hi:[0,1]
	v_pk_add_f32 v[94:95], v[198:199], v[94:95] op_sel:[1,0] op_sel_hi:[0,1]
	v_cvt_pk_bf16_f32 v92, v96, v94
	ds_write_b16 v206, v84 offset:24576
	ds_write_b16_d16_hi v206, v84 offset:24832
	ds_write_b16 v206, v92 offset:25088
	ds_write_b16_d16_hi v206, v92 offset:25344
	v_cvt_pk_bf16_f32 v84, v99, v101
	v_pk_mul_f32 v[98:99], v[136:137], v[138:139]
	v_pk_fma_f32 v[110:111], v[168:169], v[138:139], v[170:171]
	v_pk_mul_f32 v[100:101], v[98:99], v[130:131]
	v_cvt_pk_bf16_f32 v92, v97, v95
	v_pk_fma_f32 v[98:99], v[166:167], v[98:99], v[110:111]
	v_pk_mul_f32 v[96:97], v[100:101], v[128:129]
	v_mov_b32_e32 v140, v122
	v_mov_b32_e32 v142, v122
	v_mov_b32_e32 v141, v123
	v_mov_b32_e32 v143, v123
	v_pk_fma_f32 v[110:111], v[164:165], v[100:101], v[98:99]
	v_pk_mul_f32 v[98:99], v[196:197], v[96:97]
	v_permlane16_swap_b32_e32 v140, v142
	v_permlane16_swap_b32_e32 v141, v143
	v_mov_b32_e32 v197, v98
	v_mov_b32_e32 v144, v140
	v_mov_b32_e32 v146, v142
	v_mov_b32_e32 v145, v141
	v_mov_b32_e32 v147, v143
	v_pk_mul_f32 v[120:121], v[110:111], v[196:197]
	v_permlane32_swap_b32_e32 v140, v144
	v_permlane32_swap_b32_e32 v142, v146
	v_permlane32_swap_b32_e32 v141, v145
	v_permlane32_swap_b32_e32 v143, v147
	v_pk_mul_f32 v[120:121], v[120:121], s[16:17] op_sel_hi:[1,0]
	v_pk_fma_f32 v[106:107], v[136:137], v[146:147], v[144:145]
	v_pk_mul_f32 v[124:125], v[116:117], v[120:121]
	ds_write_b16 v206, v84 offset:28672
	ds_write_b16_d16_hi v206, v84 offset:28928
	ds_write_b16 v206, v92 offset:29184
	ds_write_b16_d16_hi v206, v92 offset:29440
	v_pk_fma_f32 v[108:109], v[106:107], v[130:131], v[142:143]
	v_pk_mul_f32 v[126:127], v[112:113], v[120:121]
	v_cvt_pk_u8_f32 v84, v124, 0, 0
	v_pk_fma_f32 v[94:95], v[108:109], v[128:129], v[140:141]
	v_pk_mul_f32 v[128:129], v[114:115], v[120:121]
	v_cvt_pk_u8_f32 v84, v126, 1, v84
	v_pk_mul_f32 v[120:121], v[86:87], v[120:121]
	v_cvt_pk_u8_f32 v84, v128, 2, v84
	v_cvt_pk_u8_f32 v84, v120, 3, v84
	v_pk_mul_f32 v[106:107], v[166:167], v[106:107]
	s_nop 1
	v_mov_b32_dpp v253, v84 quad_perm:[1,0,3,2] row_mask:0xf bank_mask:0xf
	v_perm_b32 v84, v253, v84, v251
	s_nop 1
	v_mov_b32_dpp v253, v84 quad_perm:[2,3,0,1] row_mask:0xf bank_mask:0xf
	v_perm_b32 v84, v253, v84, v252
	ds_write_b32 v250, v84 offset:51200
	v_cvt_pk_u8_f32 v84, v125, 0, 0
	v_pk_fma_f32 v[106:107], v[168:169], v[146:147], v[106:107]
	v_fma_f32 v101, v193, v96, v94
	v_cvt_pk_u8_f32 v84, v127, 1, v84
	v_pk_fma_f32 v[106:107], v[164:165], v[108:109], v[106:107]
	v_mov_b32_e32 v100, v193
	v_cvt_pk_u8_f32 v84, v129, 2, v84
	v_pk_fma_f32 v[106:107], v[110:111], v[100:101], v[106:107]
	v_cvt_pk_u8_f32 v84, v121, 3, v84
	v_pk_fma_f32 v[86:87], v[86:87], v[106:107], v[102:103]
	v_pk_fma_f32 v[102:103], v[114:115], v[106:107], v[118:119]
	v_pk_fma_f32 v[104:105], v[112:113], v[106:107], v[104:105]
	v_pk_fma_f32 v[106:107], v[116:117], v[106:107], v[122:123]
	s_nop 1
	v_mov_b32_dpp v253, v84 quad_perm:[1,0,3,2] row_mask:0xf bank_mask:0xf
	v_perm_b32 v84, v253, v84, v251
	s_nop 1
	v_mov_b32_dpp v253, v84 quad_perm:[2,3,0,1] row_mask:0xf bank_mask:0xf
	v_perm_b32 v84, v253, v84, v252
	ds_write_b32 v250, v84 offset:49152
	v_pk_add_f32 v[106:107], v[188:189], v[106:107] op_sel:[1,0] op_sel_hi:[0,1]
	v_pk_add_f32 v[104:105], v[186:187], v[104:105] op_sel:[1,0] op_sel_hi:[0,1]
	v_pk_add_f32 v[86:87], v[182:183], v[86:87] op_sel:[1,0] op_sel_hi:[0,1]
	v_cvt_pk_bf16_f32 v84, v106, v104
	v_pk_add_f32 v[102:103], v[184:185], v[102:103] op_sel:[1,0] op_sel_hi:[0,1]
	v_cvt_pk_bf16_f32 v86, v102, v86
	ds_write_b16 v206, v84 offset:20480
	ds_write_b16_d16_hi v206, v84 offset:20736
	ds_write_b16 v206, v86 offset:20992
	ds_write_b16_d16_hi v206, v86 offset:21248
	v_cvt_pk_bf16_f32 v84, v107, v105
	v_cvt_pk_bf16_f32 v86, v103, v87
	ds_write_b16 v206, v84 offset:16384
	ds_write_b16_d16_hi v206, v84 offset:16640
	ds_write_b16 v206, v86 offset:16896
	ds_write_b16_d16_hi v206, v86 offset:17152
	s_waitcnt vmcnt(0)
	s_and_saveexec_b64 s[20:21], s[0:1]
	s_cbranch_execz .LBB0_615
	s_mul_hi_i32 s2, s8, 0x5000
	s_mulk_i32 s8, 0x5000
	s_add_u32 s34, s9, s8
	v_fmac_f32_e32 v85, v89, v93
	v_pk_mul_f32 v[86:87], v[88:89], v[90:91] op_sel:[1,0] op_sel_hi:[0,1]
	s_addc_u32 s35, s12, s2
	v_mov_b32_e32 v87, v85
	v_lshl_add_u64 v[84:85], v[148:149], 3, s[34:35]
	v_fmac_f32_e32 v95, v97, v101
	global_store_dwordx2 v[84:85], v[86:87], off
	v_pk_mul_f32 v[86:87], v[96:97], v[98:99] op_sel:[1,0] op_sel_hi:[0,1]
	v_add_co_u32_e32 v84, vcc, 0x2000, v84
	v_mov_b32_e32 v87, v95
	s_nop 0
	v_addc_co_u32_e32 v85, vcc, 0, v85, vcc
	global_store_dwordx2 v[84:85], v[86:87], off offset:2048
	s_branch .LBB0_615
